# remove redundant duplicate lgkmcnt(0) waits in GEMM phases so every 16-MFMA group starts 8-byte aligned
# baseline (speedup 1.0000x reference)
; #define PG8_STAGE(bufoff, gbase, voff) do { _Pragma("unroll") for (int _i = 0; _i < 2; ++_i) \
;     __builtin_amdgcn_global_load_lds((const unsigned*)((const char*)(gbase) + (voff)[_i]), (PG8_LAS unsigned*)(lds + (bufoff) + ldsw + _i * 8192), 16, 0, 0); } while (0)
; #define PG8_LDA(dst, b, h) do { _Pragma("unroll") for (int m = 0; m < 4; ++m) _Pragma("unroll") for (int k = 0; k < 2; ++k) dst[m][k] = *(const PG8_LAS bf16x8*)(lds + PG8_SA(b, h) + aoff + m * 2048 + k * 1024); } while (0)
; #define PG8_LDB(dst, b, h) do { _Pragma("unroll") for (int n = 0; n < 2; ++n) _Pragma("unroll") for (int k = 0; k < 2; ++k) dst[n][k] = *(const PG8_LAS bf16x8*)(lds + PG8_SB(b, h) + boff + n * 2048 + k * 1024); } while (0)
; template <class Epi>
; DI void gemm_phase(const bf16_t* __restrict__ gA, const bf16_t* __restrict__ gBt, int M, int N, int K, const Epi& E, char* lds_generic) {
;     ...
;     for (int t = 0; t < nt; t += 2) {
;       const bool last = (t == nt - 2);
;       const char* a1 = cA + (size_t)(t + 1) * kstep;
;       const char* a2 = last ? nA : cA + (size_t)(t + 2) * kstep; const char* b2 = last ? nB : cB + (size_t)(t + 2) * kstep;
;       const char* a3 = a2 + kstep; const char* b3 = b2 + kstep;
;       PG8_LDB(B0, 0, 0); PG8_SCHED; PG8_LDA(At, 0, 0); PG8_STAGE(PG8_SA(1, 1), a1 + hstep, voffA);
;       PG8_WAIT_L(8); PG8_BAR; PG8_WAIT_L(0); PG8_MMA(0, 0, At, B0); PG8_BAR; PG8_SCHED;
;       PG8_LDB(B1, 0, 1); PG8_STAGE(PG8_SB(0, 0), b2, voffB);
;       PG8_BAR; PG8_WAIT_L(0); PG8_MMA(0, 1, At, B1); PG8_BAR;
;       PG8_LDA(At, 0, 1); PG8_STAGE(PG8_SA(0, 0), a2, voffA);
;       PG8_BAR; PG8_WAIT_L(0); PG8_MMA(1, 0, At, B0); PG8_BAR; PG8_SCHED;
;       PG8_STAGE(PG8_SB(0, 1), b2 + hstep, voffB);
;       PG8_WAIT_V(6); PG8_BAR; PG8_MMA(1, 1, At, B1); PG8_BAR;
;       PG8_LDB(B0, 1, 0); PG8_SCHED; PG8_LDA(At, 1, 0); PG8_STAGE(PG8_SA(0, 1), a2 + hstep, voffA);
;       PG8_WAIT_L(8); PG8_BAR; PG8_WAIT_L(0); PG8_MMA(0, 0, At, B0); PG8_BAR; PG8_SCHED;
;       PG8_LDB(B1, 1, 1); PG8_STAGE(PG8_SB(1, 0), b3, voffB);
;       PG8_BAR; PG8_WAIT_L(0); PG8_MMA(0, 1, At, B1); PG8_BAR;
;       PG8_LDA(At, 1, 1); PG8_STAGE(PG8_SA(1, 0), a3, voffA);
;       PG8_BAR; PG8_WAIT_L(0); PG8_MMA(1, 0, At, B0); PG8_BAR; PG8_SCHED;
;       PG8_STAGE(PG8_SB(1, 1), b3 + hstep, voffB);
;       PG8_WAIT_V(6); PG8_BAR; PG8_MMA(1, 1, At, B1); PG8_BAR;
.LBB0_137:
	ds_read_b128 v[130:133], v157
	ds_read_b128 v[146:149], v158
	ds_read_b128 v[176:179], v159
	ds_read_b128 v[180:183], v160
	s_add_u32 s24, s80, 0xfffc0080
	s_addc_u32 s25, s81, -1
	s_cmp_eq_u32 s62, 12
	s_cselect_b32 s31, s22, s25
	s_cselect_b32 s30, s23, s24
	s_cselect_b32 s29, s1, s61
	s_cselect_b32 s28, s27, s60
	s_mov_b32 m0, s33
	ds_read_b128 v[184:187], v154
	ds_read_b128 v[188:191], v154 offset:1024
	ds_read_b128 v[192:195], v154 offset:2048
	ds_read_b128 v[196:199], v154 offset:3072
	ds_read_b128 v[200:203], v154 offset:4096
	ds_read_b128 v[204:207], v154 offset:5120
	ds_read_b128 v[208:211], v154 offset:6144
	ds_read_b128 v[212:215], v154 offset:7168
	global_load_lds_dwordx4 v142, s[80:81]
	s_mov_b32 m0, s35
	s_nop 0
	global_load_lds_dwordx4 v144, s[80:81]
	s_barrier
	s_waitcnt lgkmcnt(0)
	v_mfma_f32_16x16x32_bf16 v[126:129], v[130:133], v[184:187], v[126:129]
	v_mfma_f32_16x16x32_bf16 v[122:125], v[176:179], v[184:187], v[122:125]
	v_mfma_f32_16x16x32_bf16 v[118:121], v[130:133], v[192:195], v[118:121]
	v_mfma_f32_16x16x32_bf16 v[110:113], v[176:179], v[192:195], v[110:113]
	v_mfma_f32_16x16x32_bf16 v[98:101], v[130:133], v[200:203], v[98:101]
	v_mfma_f32_16x16x32_bf16 v[90:93], v[176:179], v[200:203], v[90:93]
	v_mfma_f32_16x16x32_bf16 v[86:89], v[130:133], v[208:211], v[86:89]
	v_mfma_f32_16x16x32_bf16 v[78:81], v[176:179], v[208:211], v[78:81]
	v_mfma_f32_16x16x32_bf16 v[126:129], v[146:149], v[188:191], v[126:129]
	v_mfma_f32_16x16x32_bf16 v[122:125], v[180:183], v[188:191], v[122:125]
	v_mfma_f32_16x16x32_bf16 v[118:121], v[146:149], v[196:199], v[118:121]
	v_mfma_f32_16x16x32_bf16 v[110:113], v[180:183], v[196:199], v[110:113]
	v_mfma_f32_16x16x32_bf16 v[98:101], v[146:149], v[204:207], v[98:101]
	v_mfma_f32_16x16x32_bf16 v[90:93], v[180:183], v[204:207], v[90:93]
	v_mfma_f32_16x16x32_bf16 v[86:89], v[146:149], v[212:215], v[86:89]
	v_mfma_f32_16x16x32_bf16 v[78:81], v[180:183], v[212:215], v[78:81]
	s_barrier
	s_mov_b32 m0, s6
	ds_read_b128 v[216:219], v161
	ds_read_b128 v[238:241], v163
	ds_read_b128 v[242:245], v165
	ds_read_b128 v[246:249], v166
	global_load_lds_dwordx4 v0, s[28:29]
	s_mov_b32 m0, s7
	s_nop 0
	global_load_lds_dwordx4 v138, s[28:29]
	s_barrier
	s_waitcnt lgkmcnt(0)
	v_mfma_f32_16x16x32_bf16 v[114:117], v[216:219], v[184:187], v[114:117]
	v_mfma_f32_16x16x32_bf16 v[106:109], v[242:245], v[184:187], v[106:109]
	v_mfma_f32_16x16x32_bf16 v[102:105], v[216:219], v[192:195], v[102:105]
	v_mfma_f32_16x16x32_bf16 v[94:97], v[242:245], v[192:195], v[94:97]
	v_mfma_f32_16x16x32_bf16 v[82:85], v[216:219], v[200:203], v[82:85]
	v_mfma_f32_16x16x32_bf16 v[74:77], v[242:245], v[200:203], v[74:77]
	v_mfma_f32_16x16x32_bf16 v[70:73], v[216:219], v[208:211], v[70:73]
	v_mfma_f32_16x16x32_bf16 v[66:69], v[242:245], v[208:211], v[66:69]
	v_mfma_f32_16x16x32_bf16 v[114:117], v[238:241], v[188:191], v[114:117]
	v_mfma_f32_16x16x32_bf16 v[106:109], v[246:249], v[188:191], v[106:109]
	v_mfma_f32_16x16x32_bf16 v[102:105], v[238:241], v[196:199], v[102:105]
	v_mfma_f32_16x16x32_bf16 v[94:97], v[246:249], v[196:199], v[94:97]
	v_mfma_f32_16x16x32_bf16 v[82:85], v[238:241], v[204:207], v[82:85]
	v_mfma_f32_16x16x32_bf16 v[74:77], v[246:249], v[204:207], v[74:77]
	v_mfma_f32_16x16x32_bf16 v[70:73], v[238:241], v[212:215], v[70:73]
	v_mfma_f32_16x16x32_bf16 v[66:69], v[246:249], v[212:215], v[66:69]
	s_mov_b32 m0, s5
	s_barrier
	ds_read_b128 v[184:187], v154 offset:16384
	ds_read_b128 v[188:191], v154 offset:17408
	ds_read_b128 v[192:195], v154 offset:18432
	ds_read_b128 v[196:199], v154 offset:19456
	ds_read_b128 v[200:203], v154 offset:20480
	ds_read_b128 v[204:207], v154 offset:21504
	ds_read_b128 v[208:211], v154 offset:22528
	ds_read_b128 v[212:215], v154 offset:23552
	global_load_lds_dwordx4 v134, s[30:31]
	s_mov_b32 m0, s8
	s_nop 0
	global_load_lds_dwordx4 v136, s[30:31]
	s_barrier
	s_waitcnt lgkmcnt(0)
	v_mfma_f32_16x16x32_bf16 v[62:65], v[130:133], v[184:187], v[62:65]
	v_mfma_f32_16x16x32_bf16 v[58:61], v[176:179], v[184:187], v[58:61]
	v_mfma_f32_16x16x32_bf16 v[54:57], v[130:133], v[192:195], v[54:57]
	v_mfma_f32_16x16x32_bf16 v[46:49], v[176:179], v[192:195], v[46:49]
	v_mfma_f32_16x16x32_bf16 v[34:37], v[130:133], v[200:203], v[34:37]
	v_mfma_f32_16x16x32_bf16 v[26:29], v[176:179], v[200:203], v[26:29]
	v_mfma_f32_16x16x32_bf16 v[22:25], v[130:133], v[208:211], v[22:25]
	v_mfma_f32_16x16x32_bf16 v[14:17], v[176:179], v[208:211], v[14:17]
	v_mfma_f32_16x16x32_bf16 v[62:65], v[146:149], v[188:191], v[62:65]
	v_mfma_f32_16x16x32_bf16 v[58:61], v[180:183], v[188:191], v[58:61]
	v_mfma_f32_16x16x32_bf16 v[54:57], v[146:149], v[196:199], v[54:57]
	v_mfma_f32_16x16x32_bf16 v[46:49], v[180:183], v[196:199], v[46:49]
	v_mfma_f32_16x16x32_bf16 v[34:37], v[146:149], v[204:207], v[34:37]
	v_mfma_f32_16x16x32_bf16 v[26:29], v[180:183], v[204:207], v[26:29]
	v_mfma_f32_16x16x32_bf16 v[22:25], v[146:149], v[212:215], v[22:25]
	v_mfma_f32_16x16x32_bf16 v[14:17], v[180:183], v[212:215], v[14:17]
	s_barrier
	s_add_u32 s82, s28, 0x40000
	s_addc_u32 s83, s29, 0
	s_mov_b32 m0, s9
	s_nop 0
	global_load_lds_dwordx4 v0, s[82:83]
	s_mov_b32 m0, s12
	s_nop 0
	global_load_lds_dwordx4 v138, s[82:83]
	s_waitcnt vmcnt(6)
	s_barrier
; #define PG8_STAGE(bufoff, gbase, voff) do { _Pragma("unroll") for (int _i = 0; _i < 2; ++_i) \
;     __builtin_amdgcn_global_load_lds((const unsigned*)((const char*)(gbase) + (voff)[_i]), (PG8_LAS unsigned*)(lds + (bufoff) + ldsw + _i * 8192), 16, 0, 0); } while (0)
; #define PG8_LDA(dst, b, h) do { _Pragma("unroll") for (int m = 0; m < 4; ++m) _Pragma("unroll") for (int k = 0; k < 2; ++k) dst[m][k] = *(const PG8_LAS bf16x8*)(lds + PG8_SA(b, h) + aoff + m * 2048 + k * 1024); } while (0)
; #define PG8_LDB(dst, b, h) do { _Pragma("unroll") for (int n = 0; n < 2; ++n) _Pragma("unroll") for (int k = 0; k < 2; ++k) dst[n][k] = *(const PG8_LAS bf16x8*)(lds + PG8_SB(b, h) + boff + n * 2048 + k * 1024); } while (0)
; template <class Epi>
; DI void gemm_phase(const bf16_t* __restrict__ gA, const bf16_t* __restrict__ gBt, int M, int N, int K, const Epi& E, char* lds_generic) {
;     ...
;     for (int t = 0; t < nt; t += 2) {
;       const bool last = (t == nt - 2);
;       const char* a1 = cA + (size_t)(t + 1) * kstep;
;       const char* a2 = last ? nA : cA + (size_t)(t + 2) * kstep; const char* b2 = last ? nB : cB + (size_t)(t + 2) * kstep;
;       const char* a3 = a2 + kstep; const char* b3 = b2 + kstep;
;       PG8_LDB(B0, 0, 0); PG8_SCHED; PG8_LDA(At, 0, 0); PG8_STAGE(PG8_SA(1, 1), a1 + hstep, voffA);
;       PG8_WAIT_L(8); PG8_BAR; PG8_WAIT_L(0); PG8_MMA(0, 0, At, B0); PG8_BAR; PG8_SCHED;
;       PG8_LDB(B1, 0, 1); PG8_STAGE(PG8_SB(0, 0), b2, voffB);
;       PG8_BAR; PG8_WAIT_L(0); PG8_MMA(0, 1, At, B1); PG8_BAR;
;       PG8_LDA(At, 0, 1); PG8_STAGE(PG8_SA(0, 0), a2, voffA);
;       PG8_BAR; PG8_WAIT_L(0); PG8_MMA(1, 0, At, B0); PG8_BAR; PG8_SCHED;
;       PG8_STAGE(PG8_SB(0, 1), b2 + hstep, voffB);
;       PG8_WAIT_V(6); PG8_BAR; PG8_MMA(1, 1, At, B1); PG8_BAR;
;       PG8_LDB(B0, 1, 0); PG8_SCHED; PG8_LDA(At, 1, 0); PG8_STAGE(PG8_SA(0, 1), a2 + hstep, voffA);
;       PG8_WAIT_L(8); PG8_BAR; PG8_WAIT_L(0); PG8_MMA(0, 0, At, B0); PG8_BAR; PG8_SCHED;
;       PG8_LDB(B1, 1, 1); PG8_STAGE(PG8_SB(1, 0), b3, voffB);
;       PG8_BAR; PG8_WAIT_L(0); PG8_MMA(0, 1, At, B1); PG8_BAR;
;       PG8_LDA(At, 1, 1); PG8_STAGE(PG8_SA(1, 0), a3, voffA);
;       PG8_BAR; PG8_WAIT_L(0); PG8_MMA(1, 0, At, B0); PG8_BAR; PG8_SCHED;
;       PG8_STAGE(PG8_SB(1, 1), b3 + hstep, voffB);
;       PG8_WAIT_V(6); PG8_BAR; PG8_MMA(1, 1, At, B1); PG8_BAR;
	v_mfma_f32_16x16x32_bf16 v[50:53], v[216:219], v[184:187], v[50:53]
	v_mfma_f32_16x16x32_bf16 v[42:45], v[242:245], v[184:187], v[42:45]
	v_mfma_f32_16x16x32_bf16 v[38:41], v[216:219], v[192:195], v[38:41]
	v_mfma_f32_16x16x32_bf16 v[30:33], v[242:245], v[192:195], v[30:33]
	v_mfma_f32_16x16x32_bf16 v[18:21], v[216:219], v[200:203], v[18:21]
	v_mfma_f32_16x16x32_bf16 v[10:13], v[242:245], v[200:203], v[10:13]
	v_mfma_f32_16x16x32_bf16 v[6:9], v[216:219], v[208:211], v[6:9]
	v_mfma_f32_16x16x32_bf16 v[2:5], v[242:245], v[208:211], v[2:5]
	v_mfma_f32_16x16x32_bf16 v[50:53], v[238:241], v[188:191], v[50:53]
	v_mfma_f32_16x16x32_bf16 v[42:45], v[246:249], v[188:191], v[42:45]
	v_mfma_f32_16x16x32_bf16 v[38:41], v[238:241], v[196:199], v[38:41]
	v_mfma_f32_16x16x32_bf16 v[30:33], v[246:249], v[196:199], v[30:33]
	v_mfma_f32_16x16x32_bf16 v[18:21], v[238:241], v[204:207], v[18:21]
	v_mfma_f32_16x16x32_bf16 v[10:13], v[246:249], v[204:207], v[10:13]
	v_mfma_f32_16x16x32_bf16 v[6:9], v[238:241], v[212:215], v[6:9]
	v_mfma_f32_16x16x32_bf16 v[2:5], v[246:249], v[212:215], v[2:5]
	s_barrier
	ds_read_b128 v[130:133], v167
	ds_read_b128 v[146:149], v168
	ds_read_b128 v[176:179], v169
	ds_read_b128 v[180:183], v170
	s_add_u32 s30, s30, 0x40000
	s_addc_u32 s31, s31, 0
	s_mov_b32 m0, s13
	ds_read_b128 v[184:187], v154 offset:32768
	ds_read_b128 v[188:191], v154 offset:33792
	ds_read_b128 v[192:195], v154 offset:34816
	ds_read_b128 v[196:199], v154 offset:35840
	ds_read_b128 v[200:203], v154 offset:36864
	ds_read_b128 v[204:207], v154 offset:37888
	ds_read_b128 v[208:211], v154 offset:38912
	ds_read_b128 v[212:215], v154 offset:39936
	global_load_lds_dwordx4 v134, s[30:31]
	s_mov_b32 m0, s14
	s_nop 0
	global_load_lds_dwordx4 v136, s[30:31]
	s_barrier
	s_waitcnt lgkmcnt(0)
	s_waitcnt lgkmcnt(0)
	v_mfma_f32_16x16x32_bf16 v[126:129], v[130:133], v[184:187], v[126:129]
	v_mfma_f32_16x16x32_bf16 v[122:125], v[176:179], v[184:187], v[122:125]
	v_mfma_f32_16x16x32_bf16 v[118:121], v[130:133], v[192:195], v[118:121]
	v_mfma_f32_16x16x32_bf16 v[110:113], v[176:179], v[192:195], v[110:113]
	v_mfma_f32_16x16x32_bf16 v[98:101], v[130:133], v[200:203], v[98:101]
	v_mfma_f32_16x16x32_bf16 v[90:93], v[176:179], v[200:203], v[90:93]
	v_mfma_f32_16x16x32_bf16 v[86:89], v[130:133], v[208:211], v[86:89]
	v_mfma_f32_16x16x32_bf16 v[78:81], v[176:179], v[208:211], v[78:81]
	v_mfma_f32_16x16x32_bf16 v[126:129], v[146:149], v[188:191], v[126:129]
	v_mfma_f32_16x16x32_bf16 v[122:125], v[180:183], v[188:191], v[122:125]
	v_mfma_f32_16x16x32_bf16 v[118:121], v[146:149], v[196:199], v[118:121]
	v_mfma_f32_16x16x32_bf16 v[110:113], v[180:183], v[196:199], v[110:113]
	v_mfma_f32_16x16x32_bf16 v[98:101], v[146:149], v[204:207], v[98:101]
	v_mfma_f32_16x16x32_bf16 v[90:93], v[180:183], v[204:207], v[90:93]
	v_mfma_f32_16x16x32_bf16 v[86:89], v[146:149], v[212:215], v[86:89]
	v_mfma_f32_16x16x32_bf16 v[78:81], v[180:183], v[212:215], v[78:81]
	s_barrier
	s_mov_b32 m0, s15
	ds_read_b128 v[216:219], v171
	ds_read_b128 v[238:241], v172
	ds_read_b128 v[242:245], v173
	ds_read_b128 v[246:249], v174
	s_add_u32 s82, s28, 0x80
	s_addc_u32 s83, s29, 0
	global_load_lds_dwordx4 v0, s[82:83]
	s_mov_b32 m0, s16
	s_nop 0
	s_add_u32 s82, s28, 0x80
	s_addc_u32 s83, s29, 0
	global_load_lds_dwordx4 v138, s[82:83]
	s_barrier
	s_waitcnt lgkmcnt(0)
	v_mfma_f32_16x16x32_bf16 v[114:117], v[216:219], v[184:187], v[114:117]
	v_mfma_f32_16x16x32_bf16 v[106:109], v[242:245], v[184:187], v[106:109]
	v_mfma_f32_16x16x32_bf16 v[102:105], v[216:219], v[192:195], v[102:105]
	v_mfma_f32_16x16x32_bf16 v[94:97], v[242:245], v[192:195], v[94:97]
	v_mfma_f32_16x16x32_bf16 v[82:85], v[216:219], v[200:203], v[82:85]
	v_mfma_f32_16x16x32_bf16 v[74:77], v[242:245], v[200:203], v[74:77]
	v_mfma_f32_16x16x32_bf16 v[70:73], v[216:219], v[208:211], v[70:73]
	v_mfma_f32_16x16x32_bf16 v[66:69], v[242:245], v[208:211], v[66:69]
	v_mfma_f32_16x16x32_bf16 v[114:117], v[238:241], v[188:191], v[114:117]
	v_mfma_f32_16x16x32_bf16 v[106:109], v[246:249], v[188:191], v[106:109]
	v_mfma_f32_16x16x32_bf16 v[102:105], v[238:241], v[196:199], v[102:105]
	v_mfma_f32_16x16x32_bf16 v[94:97], v[246:249], v[196:199], v[94:97]
	v_mfma_f32_16x16x32_bf16 v[82:85], v[238:241], v[204:207], v[82:85]
	v_mfma_f32_16x16x32_bf16 v[74:77], v[246:249], v[204:207], v[74:77]
	v_mfma_f32_16x16x32_bf16 v[70:73], v[238:241], v[212:215], v[70:73]
	v_mfma_f32_16x16x32_bf16 v[66:69], v[246:249], v[212:215], v[66:69]
	s_mov_b32 m0, s18
	s_barrier
; #define PG8_STAGE(bufoff, gbase, voff) do { _Pragma("unroll") for (int _i = 0; _i < 2; ++_i) \
;     __builtin_amdgcn_global_load_lds((const unsigned*)((const char*)(gbase) + (voff)[_i]), (PG8_LAS unsigned*)(lds + (bufoff) + ldsw + _i * 8192), 16, 0, 0); } while (0)
; #define PG8_LDA(dst, b, h) do { _Pragma("unroll") for (int m = 0; m < 4; ++m) _Pragma("unroll") for (int k = 0; k < 2; ++k) dst[m][k] = *(const PG8_LAS bf16x8*)(lds + PG8_SA(b, h) + aoff + m * 2048 + k * 1024); } while (0)
; #define PG8_WAIT_V(n) asm volatile("s_waitcnt vmcnt(" #n ")" ::: "memory")
; #define PG8_WAIT_L(n) asm volatile("s_waitcnt lgkmcnt(" #n ")" ::: "memory")
; template <class Epi>
; DI void gemm_phase(const bf16_t* __restrict__ gA, const bf16_t* __restrict__ gBt, int M, int N, int K, const Epi& E, char* lds_generic) {
;     ...
;     for (int t = 0; t < nt; t += 2) {
;       const bool last = (t == nt - 2);
;       const char* a1 = cA + (size_t)(t + 1) * kstep;
;       const char* a2 = last ? nA : cA + (size_t)(t + 2) * kstep; const char* b2 = last ? nB : cB + (size_t)(t + 2) * kstep;
;       const char* a3 = a2 + kstep; const char* b3 = b2 + kstep;
;       PG8_LDB(B0, 0, 0); PG8_SCHED; PG8_LDA(At, 0, 0); PG8_STAGE(PG8_SA(1, 1), a1 + hstep, voffA);
;       PG8_WAIT_L(8); PG8_BAR; PG8_WAIT_L(0); PG8_MMA(0, 0, At, B0); PG8_BAR; PG8_SCHED;
;       PG8_LDB(B1, 0, 1); PG8_STAGE(PG8_SB(0, 0), b2, voffB);
;       PG8_BAR; PG8_WAIT_L(0); PG8_MMA(0, 1, At, B1); PG8_BAR;
;       PG8_LDA(At, 0, 1); PG8_STAGE(PG8_SA(0, 0), a2, voffA);
;       PG8_BAR; PG8_WAIT_L(0); PG8_MMA(1, 0, At, B0); PG8_BAR; PG8_SCHED;
;       PG8_STAGE(PG8_SB(0, 1), b2 + hstep, voffB);
;       PG8_WAIT_V(6); PG8_BAR; PG8_MMA(1, 1, At, B1); PG8_BAR;
;       PG8_LDB(B0, 1, 0); PG8_SCHED; PG8_LDA(At, 1, 0); PG8_STAGE(PG8_SA(0, 1), a2 + hstep, voffA);
;       PG8_WAIT_L(8); PG8_BAR; PG8_WAIT_L(0); PG8_MMA(0, 0, At, B0); PG8_BAR; PG8_SCHED;
;       PG8_LDB(B1, 1, 1); PG8_STAGE(PG8_SB(1, 0), b3, voffB);
;       PG8_BAR; PG8_WAIT_L(0); PG8_MMA(0, 1, At, B1); PG8_BAR;
;       PG8_LDA(At, 1, 1); PG8_STAGE(PG8_SA(1, 0), a3, voffA);
;       PG8_BAR; PG8_WAIT_L(0); PG8_MMA(1, 0, At, B0); PG8_BAR; PG8_SCHED;
;       PG8_STAGE(PG8_SB(1, 1), b3 + hstep, voffB);
;       PG8_WAIT_V(6); PG8_BAR; PG8_MMA(1, 1, At, B1); PG8_BAR;
;     }
;     uint4 rtn_ = {0u, 0u, 0u, 0u};
;     if (has_next) PG8_RTAB_LOAD(rtn_, nxt);
	ds_read_b128 v[184:187], v154 offset:49152
	ds_read_b128 v[188:191], v154 offset:50176
	ds_read_b128 v[192:195], v154 offset:51200
	ds_read_b128 v[196:199], v154 offset:52224
	ds_read_b128 v[200:203], v154 offset:53248
	ds_read_b128 v[204:207], v154 offset:54272
	ds_read_b128 v[208:211], v154 offset:55296
	ds_read_b128 v[212:215], v154 offset:56320
	s_add_u32 s82, s30, 0xfffc0080
	s_addc_u32 s83, s31, -1
	global_load_lds_dwordx4 v134, s[82:83]
	s_mov_b32 m0, s19
	s_nop 0
	s_add_u32 s82, s30, 0xfffc0080
	s_addc_u32 s83, s31, -1
	global_load_lds_dwordx4 v136, s[82:83]
	s_barrier
	s_waitcnt lgkmcnt(0)
	v_mfma_f32_16x16x32_bf16 v[62:65], v[130:133], v[184:187], v[62:65]
	v_mfma_f32_16x16x32_bf16 v[58:61], v[176:179], v[184:187], v[58:61]
	v_mfma_f32_16x16x32_bf16 v[54:57], v[130:133], v[192:195], v[54:57]
	v_mfma_f32_16x16x32_bf16 v[46:49], v[176:179], v[192:195], v[46:49]
	v_mfma_f32_16x16x32_bf16 v[34:37], v[130:133], v[200:203], v[34:37]
	v_mfma_f32_16x16x32_bf16 v[26:29], v[176:179], v[200:203], v[26:29]
	v_mfma_f32_16x16x32_bf16 v[22:25], v[130:133], v[208:211], v[22:25]
	v_mfma_f32_16x16x32_bf16 v[14:17], v[176:179], v[208:211], v[14:17]
	v_mfma_f32_16x16x32_bf16 v[62:65], v[146:149], v[188:191], v[62:65]
	v_mfma_f32_16x16x32_bf16 v[58:61], v[180:183], v[188:191], v[58:61]
	v_mfma_f32_16x16x32_bf16 v[54:57], v[146:149], v[196:199], v[54:57]
	v_mfma_f32_16x16x32_bf16 v[46:49], v[180:183], v[196:199], v[46:49]
	v_mfma_f32_16x16x32_bf16 v[34:37], v[146:149], v[204:207], v[34:37]
	v_mfma_f32_16x16x32_bf16 v[26:29], v[180:183], v[204:207], v[26:29]
	v_mfma_f32_16x16x32_bf16 v[22:25], v[146:149], v[212:215], v[22:25]
	v_mfma_f32_16x16x32_bf16 v[14:17], v[180:183], v[212:215], v[14:17]
	s_barrier
	s_add_u32 s28, s28, 0x40080
	s_addc_u32 s29, s29, 0
	s_mov_b32 m0, s20
	s_nop 0
	global_load_lds_dwordx4 v0, s[28:29]
	s_mov_b32 m0, s21
	s_nop 0
	global_load_lds_dwordx4 v138, s[28:29]
	s_waitcnt vmcnt(6)
	s_barrier
	v_mfma_f32_16x16x32_bf16 v[50:53], v[216:219], v[184:187], v[50:53]
	v_mfma_f32_16x16x32_bf16 v[42:45], v[242:245], v[184:187], v[42:45]
	v_mfma_f32_16x16x32_bf16 v[38:41], v[216:219], v[192:195], v[38:41]
	v_mfma_f32_16x16x32_bf16 v[30:33], v[242:245], v[192:195], v[30:33]
	v_mfma_f32_16x16x32_bf16 v[18:21], v[216:219], v[200:203], v[18:21]
	v_mfma_f32_16x16x32_bf16 v[10:13], v[242:245], v[200:203], v[10:13]
	v_mfma_f32_16x16x32_bf16 v[6:9], v[216:219], v[208:211], v[6:9]
	v_mfma_f32_16x16x32_bf16 v[2:5], v[242:245], v[208:211], v[2:5]
	v_mfma_f32_16x16x32_bf16 v[50:53], v[238:241], v[188:191], v[50:53]
	v_mfma_f32_16x16x32_bf16 v[42:45], v[246:249], v[188:191], v[42:45]
	v_mfma_f32_16x16x32_bf16 v[38:41], v[238:241], v[196:199], v[38:41]
	v_mfma_f32_16x16x32_bf16 v[30:33], v[246:249], v[196:199], v[30:33]
	v_mfma_f32_16x16x32_bf16 v[18:21], v[238:241], v[204:207], v[18:21]
	v_mfma_f32_16x16x32_bf16 v[10:13], v[246:249], v[204:207], v[10:13]
	v_mfma_f32_16x16x32_bf16 v[6:9], v[238:241], v[212:215], v[6:9]
	v_mfma_f32_16x16x32_bf16 v[2:5], v[246:249], v[212:215], v[2:5]
	s_add_i32 s62, s62, 2
	s_add_u32 s80, s80, 0x100
	s_addc_u32 s81, s81, 0
	s_add_u32 s60, s60, 0x100
	s_addc_u32 s61, s61, 0
	s_cmp_gt_u32 s62, 13
	s_barrier
	s_cbranch_scc0 .LBB0_137
	v_mov_b32_e32 v130, 0
	s_and_b64 vcc, exec, s[38:39]
	v_mov_b32_e32 v131, 0
	v_mov_b32_e32 v132, 0
	v_mov_b32_e32 v133, 0
	s_cbranch_vccz .LBB0_140
	v_lshl_add_u32 v130, s26, 8, v150
	v_ashrrev_i32_e32 v131, 31, v130
	v_lshlrev_b64 v[130:131], 5, v[130:131]
	v_lshl_add_u64 v[130:131], v[140:141], 0, v[130:131]
	global_load_dwordx4 v[130:133], v[130:131], off

; #define PG8_STAGE(bufoff, gbase, voff) do { _Pragma("unroll") for (int _i = 0; _i < 2; ++_i) \
;     __builtin_amdgcn_global_load_lds((const unsigned*)((const char*)(gbase) + (voff)[_i]), (PG8_LAS unsigned*)(lds + (bufoff) + ldsw + _i * 8192), 16, 0, 0); } while (0)
; #define PG8_LDA(dst, b, h) do { _Pragma("unroll") for (int m = 0; m < 4; ++m) _Pragma("unroll") for (int k = 0; k < 2; ++k) dst[m][k] = *(const PG8_LAS bf16x8*)(lds + PG8_SA(b, h) + aoff + m * 2048 + k * 1024); } while (0)
; #define PG8_LDB(dst, b, h) do { _Pragma("unroll") for (int n = 0; n < 2; ++n) _Pragma("unroll") for (int k = 0; k < 2; ++k) dst[n][k] = *(const PG8_LAS bf16x8*)(lds + PG8_SB(b, h) + boff + n * 2048 + k * 1024); } while (0)
; template <class Epi>
; DI void gemm_phase(const bf16_t* __restrict__ gA, const bf16_t* __restrict__ gBt, int M, int N, int K, const Epi& E, char* lds_generic) {
;     ...
;     for (int t = 0; t < nt; t += 2) {
;       const bool last = (t == nt - 2);
;       const char* a1 = cA + (size_t)(t + 1) * kstep;
;       const char* a2 = last ? nA : cA + (size_t)(t + 2) * kstep; const char* b2 = last ? nB : cB + (size_t)(t + 2) * kstep;
;       const char* a3 = a2 + kstep; const char* b3 = b2 + kstep;
;       PG8_LDB(B0, 0, 0); PG8_SCHED; PG8_LDA(At, 0, 0); PG8_STAGE(PG8_SA(1, 1), a1 + hstep, voffA);
;       PG8_WAIT_L(8); PG8_BAR; PG8_WAIT_L(0); PG8_MMA(0, 0, At, B0); PG8_BAR; PG8_SCHED;
;       PG8_LDB(B1, 0, 1); PG8_STAGE(PG8_SB(0, 0), b2, voffB);
;       PG8_BAR; PG8_WAIT_L(0); PG8_MMA(0, 1, At, B1); PG8_BAR;
;       PG8_LDA(At, 0, 1); PG8_STAGE(PG8_SA(0, 0), a2, voffA);
;       PG8_BAR; PG8_WAIT_L(0); PG8_MMA(1, 0, At, B0); PG8_BAR; PG8_SCHED;
;       PG8_STAGE(PG8_SB(0, 1), b2 + hstep, voffB);
;       PG8_WAIT_V(6); PG8_BAR; PG8_MMA(1, 1, At, B1); PG8_BAR;
;       PG8_LDB(B0, 1, 0); PG8_SCHED; PG8_LDA(At, 1, 0); PG8_STAGE(PG8_SA(0, 1), a2 + hstep, voffA);
;       PG8_WAIT_L(8); PG8_BAR; PG8_WAIT_L(0); PG8_MMA(0, 0, At, B0); PG8_BAR; PG8_SCHED;
;       PG8_LDB(B1, 1, 1); PG8_STAGE(PG8_SB(1, 0), b3, voffB);
;       PG8_BAR; PG8_WAIT_L(0); PG8_MMA(0, 1, At, B1); PG8_BAR;
;       PG8_LDA(At, 1, 1); PG8_STAGE(PG8_SA(1, 0), a3, voffA);
;       PG8_BAR; PG8_WAIT_L(0); PG8_MMA(1, 0, At, B0); PG8_BAR; PG8_SCHED;
;       PG8_STAGE(PG8_SB(1, 1), b3 + hstep, voffB);
;       PG8_WAIT_V(6); PG8_BAR; PG8_MMA(1, 1, At, B1); PG8_BAR;
.LBB0_159:
	ds_read_b128 v[130:133], v155
	ds_read_b128 v[146:149], v155 offset:1024
	ds_read_b128 v[158:161], v155 offset:2048
	ds_read_b128 v[166:169], v155 offset:3072
	s_add_u32 s23, s80, 0xfffc0080
	s_addc_u32 s24, s81, -1
	s_cmp_eq_u32 s22, 12
	s_cselect_b32 s31, s27, s24
	s_cselect_b32 s30, s58, s23
	s_cselect_b32 s29, s1, s61
	s_cselect_b32 s28, s59, s60
	s_add_i32 m0, s5, 0xc000
	ds_read_b128 v[170:173], v154
	ds_read_b128 v[174:177], v154 offset:1024
	ds_read_b128 v[178:181], v154 offset:2048
	ds_read_b128 v[182:185], v154 offset:3072
	ds_read_b128 v[186:189], v154 offset:4096
	ds_read_b128 v[190:193], v154 offset:5120
	ds_read_b128 v[194:197], v154 offset:6144
	ds_read_b128 v[198:201], v154 offset:7168
	global_load_lds_dwordx4 v142, s[80:81]
	s_add_i32 m0, s5, 0xe000
	s_nop 0
	global_load_lds_dwordx4 v144, s[80:81]
	s_barrier
	s_waitcnt lgkmcnt(0)
	s_waitcnt lgkmcnt(0)
	v_mfma_f32_16x16x32_bf16 v[126:129], v[130:133], v[170:173], v[126:129]
	v_mfma_f32_16x16x32_bf16 v[122:125], v[158:161], v[170:173], v[122:125]
	v_mfma_f32_16x16x32_bf16 v[118:121], v[130:133], v[178:181], v[118:121]
	v_mfma_f32_16x16x32_bf16 v[110:113], v[158:161], v[178:181], v[110:113]
	v_mfma_f32_16x16x32_bf16 v[98:101], v[130:133], v[186:189], v[98:101]
	v_mfma_f32_16x16x32_bf16 v[90:93], v[158:161], v[186:189], v[90:93]
	v_mfma_f32_16x16x32_bf16 v[86:89], v[130:133], v[194:197], v[86:89]
	v_mfma_f32_16x16x32_bf16 v[78:81], v[158:161], v[194:197], v[78:81]
	v_mfma_f32_16x16x32_bf16 v[126:129], v[146:149], v[174:177], v[126:129]
	v_mfma_f32_16x16x32_bf16 v[122:125], v[166:169], v[174:177], v[122:125]
	v_mfma_f32_16x16x32_bf16 v[118:121], v[146:149], v[182:185], v[118:121]
	v_mfma_f32_16x16x32_bf16 v[110:113], v[166:169], v[182:185], v[110:113]
	v_mfma_f32_16x16x32_bf16 v[98:101], v[146:149], v[190:193], v[98:101]
	v_mfma_f32_16x16x32_bf16 v[90:93], v[166:169], v[190:193], v[90:93]
	v_mfma_f32_16x16x32_bf16 v[86:89], v[146:149], v[198:201], v[86:89]
	v_mfma_f32_16x16x32_bf16 v[78:81], v[166:169], v[198:201], v[78:81]
	s_barrier
	s_mov_b32 m0, s6
	ds_read_b128 v[202:205], v155 offset:16384
	ds_read_b128 v[206:209], v155 offset:17408
	ds_read_b128 v[210:213], v155 offset:18432
	ds_read_b128 v[214:217], v155 offset:19456
	global_load_lds_dwordx4 v0, s[28:29]
	s_mov_b32 m0, s7
	s_nop 0
	global_load_lds_dwordx4 v138, s[28:29]
	s_barrier
	s_waitcnt lgkmcnt(0)
	v_mfma_f32_16x16x32_bf16 v[114:117], v[202:205], v[170:173], v[114:117]
	v_mfma_f32_16x16x32_bf16 v[106:109], v[210:213], v[170:173], v[106:109]
	v_mfma_f32_16x16x32_bf16 v[102:105], v[202:205], v[178:181], v[102:105]
	v_mfma_f32_16x16x32_bf16 v[94:97], v[210:213], v[178:181], v[94:97]
	v_mfma_f32_16x16x32_bf16 v[82:85], v[202:205], v[186:189], v[82:85]
	v_mfma_f32_16x16x32_bf16 v[74:77], v[210:213], v[186:189], v[74:77]
	v_mfma_f32_16x16x32_bf16 v[70:73], v[202:205], v[194:197], v[70:73]
	v_mfma_f32_16x16x32_bf16 v[66:69], v[210:213], v[194:197], v[66:69]
	v_mfma_f32_16x16x32_bf16 v[114:117], v[206:209], v[174:177], v[114:117]
	v_mfma_f32_16x16x32_bf16 v[106:109], v[214:217], v[174:177], v[106:109]
	v_mfma_f32_16x16x32_bf16 v[102:105], v[206:209], v[182:185], v[102:105]
	v_mfma_f32_16x16x32_bf16 v[94:97], v[214:217], v[182:185], v[94:97]
	v_mfma_f32_16x16x32_bf16 v[82:85], v[206:209], v[190:193], v[82:85]
	v_mfma_f32_16x16x32_bf16 v[74:77], v[214:217], v[190:193], v[74:77]
	v_mfma_f32_16x16x32_bf16 v[70:73], v[206:209], v[198:201], v[70:73]
	v_mfma_f32_16x16x32_bf16 v[66:69], v[214:217], v[198:201], v[66:69]
	s_mov_b32 m0, s5
	s_barrier
	ds_read_b128 v[170:173], v154 offset:16384
	ds_read_b128 v[174:177], v154 offset:17408
	ds_read_b128 v[178:181], v154 offset:18432
	ds_read_b128 v[182:185], v154 offset:19456
	ds_read_b128 v[186:189], v154 offset:20480
	ds_read_b128 v[190:193], v154 offset:21504
	ds_read_b128 v[194:197], v154 offset:22528
	ds_read_b128 v[198:201], v154 offset:23552
	global_load_lds_dwordx4 v134, s[30:31]
	s_mov_b32 m0, s8
	s_nop 0
	global_load_lds_dwordx4 v136, s[30:31]
	s_barrier
	s_waitcnt lgkmcnt(0)
	v_mfma_f32_16x16x32_bf16 v[62:65], v[130:133], v[170:173], v[62:65]
	v_mfma_f32_16x16x32_bf16 v[58:61], v[158:161], v[170:173], v[58:61]
	v_mfma_f32_16x16x32_bf16 v[54:57], v[130:133], v[178:181], v[54:57]
	v_mfma_f32_16x16x32_bf16 v[46:49], v[158:161], v[178:181], v[46:49]
	v_mfma_f32_16x16x32_bf16 v[34:37], v[130:133], v[186:189], v[34:37]
	v_mfma_f32_16x16x32_bf16 v[26:29], v[158:161], v[186:189], v[26:29]
	v_mfma_f32_16x16x32_bf16 v[22:25], v[130:133], v[194:197], v[22:25]
	v_mfma_f32_16x16x32_bf16 v[14:17], v[158:161], v[194:197], v[14:17]
	v_mfma_f32_16x16x32_bf16 v[62:65], v[146:149], v[174:177], v[62:65]
	v_mfma_f32_16x16x32_bf16 v[58:61], v[166:169], v[174:177], v[58:61]
	v_mfma_f32_16x16x32_bf16 v[54:57], v[146:149], v[182:185], v[54:57]
	v_mfma_f32_16x16x32_bf16 v[46:49], v[166:169], v[182:185], v[46:49]
	v_mfma_f32_16x16x32_bf16 v[34:37], v[146:149], v[190:193], v[34:37]
	v_mfma_f32_16x16x32_bf16 v[26:29], v[166:169], v[190:193], v[26:29]
	v_mfma_f32_16x16x32_bf16 v[22:25], v[146:149], v[198:201], v[22:25]
	v_mfma_f32_16x16x32_bf16 v[14:17], v[166:169], v[198:201], v[14:17]
	s_barrier
	s_add_u32 s82, s28, 0x40000
	s_addc_u32 s83, s29, 0
	s_mov_b32 m0, s9
	s_nop 0
	global_load_lds_dwordx4 v0, s[82:83]
	s_mov_b32 m0, s12
	s_nop 0
	global_load_lds_dwordx4 v138, s[82:83]
	s_waitcnt vmcnt(6)
	s_barrier
; #define PG8_STAGE(bufoff, gbase, voff) do { _Pragma("unroll") for (int _i = 0; _i < 2; ++_i) \
;     __builtin_amdgcn_global_load_lds((const unsigned*)((const char*)(gbase) + (voff)[_i]), (PG8_LAS unsigned*)(lds + (bufoff) + ldsw + _i * 8192), 16, 0, 0); } while (0)
; #define PG8_LDA(dst, b, h) do { _Pragma("unroll") for (int m = 0; m < 4; ++m) _Pragma("unroll") for (int k = 0; k < 2; ++k) dst[m][k] = *(const PG8_LAS bf16x8*)(lds + PG8_SA(b, h) + aoff + m * 2048 + k * 1024); } while (0)
; #define PG8_LDB(dst, b, h) do { _Pragma("unroll") for (int n = 0; n < 2; ++n) _Pragma("unroll") for (int k = 0; k < 2; ++k) dst[n][k] = *(const PG8_LAS bf16x8*)(lds + PG8_SB(b, h) + boff + n * 2048 + k * 1024); } while (0)
; template <class Epi>
; DI void gemm_phase(const bf16_t* __restrict__ gA, const bf16_t* __restrict__ gBt, int M, int N, int K, const Epi& E, char* lds_generic) {
;     ...
;     for (int t = 0; t < nt; t += 2) {
;       const bool last = (t == nt - 2);
;       const char* a1 = cA + (size_t)(t + 1) * kstep;
;       const char* a2 = last ? nA : cA + (size_t)(t + 2) * kstep; const char* b2 = last ? nB : cB + (size_t)(t + 2) * kstep;
;       const char* a3 = a2 + kstep; const char* b3 = b2 + kstep;
;       PG8_LDB(B0, 0, 0); PG8_SCHED; PG8_LDA(At, 0, 0); PG8_STAGE(PG8_SA(1, 1), a1 + hstep, voffA);
;       PG8_WAIT_L(8); PG8_BAR; PG8_WAIT_L(0); PG8_MMA(0, 0, At, B0); PG8_BAR; PG8_SCHED;
;       PG8_LDB(B1, 0, 1); PG8_STAGE(PG8_SB(0, 0), b2, voffB);
;       PG8_BAR; PG8_WAIT_L(0); PG8_MMA(0, 1, At, B1); PG8_BAR;
;       PG8_LDA(At, 0, 1); PG8_STAGE(PG8_SA(0, 0), a2, voffA);
;       PG8_BAR; PG8_WAIT_L(0); PG8_MMA(1, 0, At, B0); PG8_BAR; PG8_SCHED;
;       PG8_STAGE(PG8_SB(0, 1), b2 + hstep, voffB);
;       PG8_WAIT_V(6); PG8_BAR; PG8_MMA(1, 1, At, B1); PG8_BAR;
;       PG8_LDB(B0, 1, 0); PG8_SCHED; PG8_LDA(At, 1, 0); PG8_STAGE(PG8_SA(0, 1), a2 + hstep, voffA);
;       PG8_WAIT_L(8); PG8_BAR; PG8_WAIT_L(0); PG8_MMA(0, 0, At, B0); PG8_BAR; PG8_SCHED;
;       PG8_LDB(B1, 1, 1); PG8_STAGE(PG8_SB(1, 0), b3, voffB);
;       PG8_BAR; PG8_WAIT_L(0); PG8_MMA(0, 1, At, B1); PG8_BAR;
;       PG8_LDA(At, 1, 1); PG8_STAGE(PG8_SA(1, 0), a3, voffA);
;       PG8_BAR; PG8_WAIT_L(0); PG8_MMA(1, 0, At, B0); PG8_BAR; PG8_SCHED;
;       PG8_STAGE(PG8_SB(1, 1), b3 + hstep, voffB);
;       PG8_WAIT_V(6); PG8_BAR; PG8_MMA(1, 1, At, B1); PG8_BAR;
	v_mfma_f32_16x16x32_bf16 v[50:53], v[202:205], v[170:173], v[50:53]
	v_mfma_f32_16x16x32_bf16 v[42:45], v[210:213], v[170:173], v[42:45]
	v_mfma_f32_16x16x32_bf16 v[38:41], v[202:205], v[178:181], v[38:41]
	v_mfma_f32_16x16x32_bf16 v[30:33], v[210:213], v[178:181], v[30:33]
	v_mfma_f32_16x16x32_bf16 v[18:21], v[202:205], v[186:189], v[18:21]
	v_mfma_f32_16x16x32_bf16 v[10:13], v[210:213], v[186:189], v[10:13]
	v_mfma_f32_16x16x32_bf16 v[6:9], v[202:205], v[194:197], v[6:9]
	v_mfma_f32_16x16x32_bf16 v[2:5], v[210:213], v[194:197], v[2:5]
	v_mfma_f32_16x16x32_bf16 v[50:53], v[206:209], v[174:177], v[50:53]
	v_mfma_f32_16x16x32_bf16 v[42:45], v[214:217], v[174:177], v[42:45]
	v_mfma_f32_16x16x32_bf16 v[38:41], v[206:209], v[182:185], v[38:41]
	v_mfma_f32_16x16x32_bf16 v[30:33], v[214:217], v[182:185], v[30:33]
	v_mfma_f32_16x16x32_bf16 v[18:21], v[206:209], v[190:193], v[18:21]
	v_mfma_f32_16x16x32_bf16 v[10:13], v[214:217], v[190:193], v[10:13]
	v_mfma_f32_16x16x32_bf16 v[6:9], v[206:209], v[198:201], v[6:9]
	v_mfma_f32_16x16x32_bf16 v[2:5], v[214:217], v[198:201], v[2:5]
	s_barrier
	ds_read_b128 v[130:133], v155 offset:32768
	ds_read_b128 v[146:149], v155 offset:33792
	ds_read_b128 v[158:161], v155 offset:34816
	ds_read_b128 v[166:169], v155 offset:35840
	s_add_u32 s30, s30, 0x40000
	s_addc_u32 s31, s31, 0
	s_mov_b32 m0, s13
	ds_read_b128 v[170:173], v154 offset:32768
	ds_read_b128 v[174:177], v154 offset:33792
	ds_read_b128 v[178:181], v154 offset:34816
	ds_read_b128 v[182:185], v154 offset:35840
	ds_read_b128 v[186:189], v154 offset:36864
	ds_read_b128 v[190:193], v154 offset:37888
	ds_read_b128 v[194:197], v154 offset:38912
	ds_read_b128 v[198:201], v154 offset:39936
	global_load_lds_dwordx4 v134, s[30:31]
	s_mov_b32 m0, s14
	s_nop 0
	global_load_lds_dwordx4 v136, s[30:31]
	s_barrier
	s_waitcnt lgkmcnt(0)
	s_waitcnt lgkmcnt(0)
	v_mfma_f32_16x16x32_bf16 v[126:129], v[130:133], v[170:173], v[126:129]
	v_mfma_f32_16x16x32_bf16 v[122:125], v[158:161], v[170:173], v[122:125]
	v_mfma_f32_16x16x32_bf16 v[118:121], v[130:133], v[178:181], v[118:121]
	v_mfma_f32_16x16x32_bf16 v[110:113], v[158:161], v[178:181], v[110:113]
	v_mfma_f32_16x16x32_bf16 v[98:101], v[130:133], v[186:189], v[98:101]
	v_mfma_f32_16x16x32_bf16 v[90:93], v[158:161], v[186:189], v[90:93]
	v_mfma_f32_16x16x32_bf16 v[86:89], v[130:133], v[194:197], v[86:89]
	v_mfma_f32_16x16x32_bf16 v[78:81], v[158:161], v[194:197], v[78:81]
	v_mfma_f32_16x16x32_bf16 v[126:129], v[146:149], v[174:177], v[126:129]
	v_mfma_f32_16x16x32_bf16 v[122:125], v[166:169], v[174:177], v[122:125]
	v_mfma_f32_16x16x32_bf16 v[118:121], v[146:149], v[182:185], v[118:121]
	v_mfma_f32_16x16x32_bf16 v[110:113], v[166:169], v[182:185], v[110:113]
	v_mfma_f32_16x16x32_bf16 v[98:101], v[146:149], v[190:193], v[98:101]
	v_mfma_f32_16x16x32_bf16 v[90:93], v[166:169], v[190:193], v[90:93]
	v_mfma_f32_16x16x32_bf16 v[86:89], v[146:149], v[198:201], v[86:89]
	v_mfma_f32_16x16x32_bf16 v[78:81], v[166:169], v[198:201], v[78:81]
	s_barrier
	s_mov_b32 m0, s15
	ds_read_b128 v[202:205], v155 offset:49152
	ds_read_b128 v[206:209], v155 offset:50176
	ds_read_b128 v[210:213], v155 offset:51200
	ds_read_b128 v[214:217], v155 offset:52224
	s_add_u32 s82, s28, 0x80
	s_addc_u32 s83, s29, 0
	global_load_lds_dwordx4 v0, s[82:83]
	s_mov_b32 m0, s16
	s_nop 0
	s_add_u32 s82, s28, 0x80
	s_addc_u32 s83, s29, 0
	global_load_lds_dwordx4 v138, s[82:83]
	s_barrier
	s_waitcnt lgkmcnt(0)
	v_mfma_f32_16x16x32_bf16 v[114:117], v[202:205], v[170:173], v[114:117]
	v_mfma_f32_16x16x32_bf16 v[106:109], v[210:213], v[170:173], v[106:109]
	v_mfma_f32_16x16x32_bf16 v[102:105], v[202:205], v[178:181], v[102:105]
	v_mfma_f32_16x16x32_bf16 v[94:97], v[210:213], v[178:181], v[94:97]
	v_mfma_f32_16x16x32_bf16 v[82:85], v[202:205], v[186:189], v[82:85]
	v_mfma_f32_16x16x32_bf16 v[74:77], v[210:213], v[186:189], v[74:77]
	v_mfma_f32_16x16x32_bf16 v[70:73], v[202:205], v[194:197], v[70:73]
	v_mfma_f32_16x16x32_bf16 v[66:69], v[210:213], v[194:197], v[66:69]
	v_mfma_f32_16x16x32_bf16 v[114:117], v[206:209], v[174:177], v[114:117]
	v_mfma_f32_16x16x32_bf16 v[106:109], v[214:217], v[174:177], v[106:109]
	v_mfma_f32_16x16x32_bf16 v[102:105], v[206:209], v[182:185], v[102:105]
	v_mfma_f32_16x16x32_bf16 v[94:97], v[214:217], v[182:185], v[94:97]
	v_mfma_f32_16x16x32_bf16 v[82:85], v[206:209], v[190:193], v[82:85]
	v_mfma_f32_16x16x32_bf16 v[74:77], v[214:217], v[190:193], v[74:77]
	v_mfma_f32_16x16x32_bf16 v[70:73], v[206:209], v[198:201], v[70:73]
	v_mfma_f32_16x16x32_bf16 v[66:69], v[214:217], v[198:201], v[66:69]
	s_mov_b32 m0, s18
	s_barrier
; #define PG8_STAGE(bufoff, gbase, voff) do { _Pragma("unroll") for (int _i = 0; _i < 2; ++_i) \
;     __builtin_amdgcn_global_load_lds((const unsigned*)((const char*)(gbase) + (voff)[_i]), (PG8_LAS unsigned*)(lds + (bufoff) + ldsw + _i * 8192), 16, 0, 0); } while (0)
; #define PG8_LDA(dst, b, h) do { _Pragma("unroll") for (int m = 0; m < 4; ++m) _Pragma("unroll") for (int k = 0; k < 2; ++k) dst[m][k] = *(const PG8_LAS bf16x8*)(lds + PG8_SA(b, h) + aoff + m * 2048 + k * 1024); } while (0)
; #define PG8_WAIT_V(n) asm volatile("s_waitcnt vmcnt(" #n ")" ::: "memory")
; #define PG8_WAIT_L(n) asm volatile("s_waitcnt lgkmcnt(" #n ")" ::: "memory")
; template <class Epi>
; DI void gemm_phase(const bf16_t* __restrict__ gA, const bf16_t* __restrict__ gBt, int M, int N, int K, const Epi& E, char* lds_generic) {
;     ...
;     for (int t = 0; t < nt; t += 2) {
;       const bool last = (t == nt - 2);
;       const char* a1 = cA + (size_t)(t + 1) * kstep;
;       const char* a2 = last ? nA : cA + (size_t)(t + 2) * kstep; const char* b2 = last ? nB : cB + (size_t)(t + 2) * kstep;
;       const char* a3 = a2 + kstep; const char* b3 = b2 + kstep;
;       PG8_LDB(B0, 0, 0); PG8_SCHED; PG8_LDA(At, 0, 0); PG8_STAGE(PG8_SA(1, 1), a1 + hstep, voffA);
;       PG8_WAIT_L(8); PG8_BAR; PG8_WAIT_L(0); PG8_MMA(0, 0, At, B0); PG8_BAR; PG8_SCHED;
;       PG8_LDB(B1, 0, 1); PG8_STAGE(PG8_SB(0, 0), b2, voffB);
;       PG8_BAR; PG8_WAIT_L(0); PG8_MMA(0, 1, At, B1); PG8_BAR;
;       PG8_LDA(At, 0, 1); PG8_STAGE(PG8_SA(0, 0), a2, voffA);
;       PG8_BAR; PG8_WAIT_L(0); PG8_MMA(1, 0, At, B0); PG8_BAR; PG8_SCHED;
;       PG8_STAGE(PG8_SB(0, 1), b2 + hstep, voffB);
;       PG8_WAIT_V(6); PG8_BAR; PG8_MMA(1, 1, At, B1); PG8_BAR;
;       PG8_LDB(B0, 1, 0); PG8_SCHED; PG8_LDA(At, 1, 0); PG8_STAGE(PG8_SA(0, 1), a2 + hstep, voffA);
;       PG8_WAIT_L(8); PG8_BAR; PG8_WAIT_L(0); PG8_MMA(0, 0, At, B0); PG8_BAR; PG8_SCHED;
;       PG8_LDB(B1, 1, 1); PG8_STAGE(PG8_SB(1, 0), b3, voffB);
;       PG8_BAR; PG8_WAIT_L(0); PG8_MMA(0, 1, At, B1); PG8_BAR;
;       PG8_LDA(At, 1, 1); PG8_STAGE(PG8_SA(1, 0), a3, voffA);
;       PG8_BAR; PG8_WAIT_L(0); PG8_MMA(1, 0, At, B0); PG8_BAR; PG8_SCHED;
;       PG8_STAGE(PG8_SB(1, 1), b3 + hstep, voffB);
;       PG8_WAIT_V(6); PG8_BAR; PG8_MMA(1, 1, At, B1); PG8_BAR;
;     }
;     uint4 rtn_ = {0u, 0u, 0u, 0u};
;     if (has_next) PG8_RTAB_LOAD(rtn_, nxt);
	ds_read_b128 v[170:173], v154 offset:49152
	ds_read_b128 v[174:177], v154 offset:50176
	ds_read_b128 v[178:181], v154 offset:51200
	ds_read_b128 v[182:185], v154 offset:52224
	ds_read_b128 v[186:189], v154 offset:53248
	ds_read_b128 v[190:193], v154 offset:54272
	ds_read_b128 v[194:197], v154 offset:55296
	ds_read_b128 v[198:201], v154 offset:56320
	s_add_u32 s82, s30, 0xfffc0080
	s_addc_u32 s83, s31, -1
	global_load_lds_dwordx4 v134, s[82:83]
	s_mov_b32 m0, s19
	s_nop 0
	s_add_u32 s82, s30, 0xfffc0080
	s_addc_u32 s83, s31, -1
	global_load_lds_dwordx4 v136, s[82:83]
	s_barrier
	s_waitcnt lgkmcnt(0)
	v_mfma_f32_16x16x32_bf16 v[62:65], v[130:133], v[170:173], v[62:65]
	v_mfma_f32_16x16x32_bf16 v[58:61], v[158:161], v[170:173], v[58:61]
	v_mfma_f32_16x16x32_bf16 v[54:57], v[130:133], v[178:181], v[54:57]
	v_mfma_f32_16x16x32_bf16 v[46:49], v[158:161], v[178:181], v[46:49]
	v_mfma_f32_16x16x32_bf16 v[34:37], v[130:133], v[186:189], v[34:37]
	v_mfma_f32_16x16x32_bf16 v[26:29], v[158:161], v[186:189], v[26:29]
	v_mfma_f32_16x16x32_bf16 v[22:25], v[130:133], v[194:197], v[22:25]
	v_mfma_f32_16x16x32_bf16 v[14:17], v[158:161], v[194:197], v[14:17]
	v_mfma_f32_16x16x32_bf16 v[62:65], v[146:149], v[174:177], v[62:65]
	v_mfma_f32_16x16x32_bf16 v[58:61], v[166:169], v[174:177], v[58:61]
	v_mfma_f32_16x16x32_bf16 v[54:57], v[146:149], v[182:185], v[54:57]
	v_mfma_f32_16x16x32_bf16 v[46:49], v[166:169], v[182:185], v[46:49]
	v_mfma_f32_16x16x32_bf16 v[34:37], v[146:149], v[190:193], v[34:37]
	v_mfma_f32_16x16x32_bf16 v[26:29], v[166:169], v[190:193], v[26:29]
	v_mfma_f32_16x16x32_bf16 v[22:25], v[146:149], v[198:201], v[22:25]
	v_mfma_f32_16x16x32_bf16 v[14:17], v[166:169], v[198:201], v[14:17]
	s_barrier
	s_add_u32 s28, s28, 0x40080
	s_addc_u32 s29, s29, 0
	s_mov_b32 m0, s20
	s_nop 0
	global_load_lds_dwordx4 v0, s[28:29]
	s_mov_b32 m0, s21
	s_nop 0
	global_load_lds_dwordx4 v138, s[28:29]
	s_waitcnt vmcnt(6)
	s_barrier
	v_mfma_f32_16x16x32_bf16 v[50:53], v[202:205], v[170:173], v[50:53]
	v_mfma_f32_16x16x32_bf16 v[42:45], v[210:213], v[170:173], v[42:45]
	v_mfma_f32_16x16x32_bf16 v[38:41], v[202:205], v[178:181], v[38:41]
	v_mfma_f32_16x16x32_bf16 v[30:33], v[210:213], v[178:181], v[30:33]
	v_mfma_f32_16x16x32_bf16 v[18:21], v[202:205], v[186:189], v[18:21]
	v_mfma_f32_16x16x32_bf16 v[10:13], v[210:213], v[186:189], v[10:13]
	v_mfma_f32_16x16x32_bf16 v[6:9], v[202:205], v[194:197], v[6:9]
	v_mfma_f32_16x16x32_bf16 v[2:5], v[210:213], v[194:197], v[2:5]
	v_mfma_f32_16x16x32_bf16 v[50:53], v[206:209], v[174:177], v[50:53]
	v_mfma_f32_16x16x32_bf16 v[42:45], v[214:217], v[174:177], v[42:45]
	v_mfma_f32_16x16x32_bf16 v[38:41], v[206:209], v[182:185], v[38:41]
	v_mfma_f32_16x16x32_bf16 v[30:33], v[214:217], v[182:185], v[30:33]
	v_mfma_f32_16x16x32_bf16 v[18:21], v[206:209], v[190:193], v[18:21]
	v_mfma_f32_16x16x32_bf16 v[10:13], v[214:217], v[190:193], v[10:13]
	v_mfma_f32_16x16x32_bf16 v[6:9], v[206:209], v[198:201], v[6:9]
	v_mfma_f32_16x16x32_bf16 v[2:5], v[214:217], v[198:201], v[2:5]
	s_add_i32 s22, s22, 2
	s_add_u32 s80, s80, 0x100
	s_addc_u32 s81, s81, 0
	s_add_u32 s60, s60, 0x100
	s_addc_u32 s61, s61, 0
	s_cmp_gt_u32 s22, 13
	s_barrier
	s_cbranch_scc0 .LBB0_159
	v_mov_b32_e32 v130, 0
	s_and_b64 vcc, exec, s[38:39]
	v_mov_b32_e32 v131, 0
	v_mov_b32_e32 v132, 0
	v_mov_b32_e32 v133, 0
	s_cbranch_vccz .LBB0_162
	v_lshl_add_u32 v130, s26, 8, v150
	v_ashrrev_i32_e32 v131, 31, v130
	v_lshlrev_b64 v[130:131], 5, v[130:131]
	v_lshl_add_u64 v[130:131], v[140:141], 0, v[130:131]
	global_load_dwordx4 v[130:133], v[130:131], off

; #define PG8_STAGE(bufoff, gbase, voff) do { _Pragma("unroll") for (int _i = 0; _i < 2; ++_i) \
;     __builtin_amdgcn_global_load_lds((const unsigned*)((const char*)(gbase) + (voff)[_i]), (PG8_LAS unsigned*)(lds + (bufoff) + ldsw + _i * 8192), 16, 0, 0); } while (0)
; #define PG8_LDA(dst, b, h) do { _Pragma("unroll") for (int m = 0; m < 4; ++m) _Pragma("unroll") for (int k = 0; k < 2; ++k) dst[m][k] = *(const PG8_LAS bf16x8*)(lds + PG8_SA(b, h) + aoff + m * 2048 + k * 1024); } while (0)
; #define PG8_LDB(dst, b, h) do { _Pragma("unroll") for (int n = 0; n < 2; ++n) _Pragma("unroll") for (int k = 0; k < 2; ++k) dst[n][k] = *(const PG8_LAS bf16x8*)(lds + PG8_SB(b, h) + boff + n * 2048 + k * 1024); } while (0)
; template <class Epi>
; DI void gemm_phase(const bf16_t* __restrict__ gA, const bf16_t* __restrict__ gBt, int M, int N, int K, const Epi& E, char* lds_generic) {
;     ...
;     for (int t = 0; t < nt; t += 2) {
;       const bool last = (t == nt - 2);
;       const char* a1 = cA + (size_t)(t + 1) * kstep;
;       const char* a2 = last ? nA : cA + (size_t)(t + 2) * kstep; const char* b2 = last ? nB : cB + (size_t)(t + 2) * kstep;
;       const char* a3 = a2 + kstep; const char* b3 = b2 + kstep;
;       PG8_LDB(B0, 0, 0); PG8_SCHED; PG8_LDA(At, 0, 0); PG8_STAGE(PG8_SA(1, 1), a1 + hstep, voffA);
;       PG8_WAIT_L(8); PG8_BAR; PG8_WAIT_L(0); PG8_MMA(0, 0, At, B0); PG8_BAR; PG8_SCHED;
;       PG8_LDB(B1, 0, 1); PG8_STAGE(PG8_SB(0, 0), b2, voffB);
;       PG8_BAR; PG8_WAIT_L(0); PG8_MMA(0, 1, At, B1); PG8_BAR;
;       PG8_LDA(At, 0, 1); PG8_STAGE(PG8_SA(0, 0), a2, voffA);
;       PG8_BAR; PG8_WAIT_L(0); PG8_MMA(1, 0, At, B0); PG8_BAR; PG8_SCHED;
;       PG8_STAGE(PG8_SB(0, 1), b2 + hstep, voffB);
;       PG8_WAIT_V(6); PG8_BAR; PG8_MMA(1, 1, At, B1); PG8_BAR;
;       PG8_LDB(B0, 1, 0); PG8_SCHED; PG8_LDA(At, 1, 0); PG8_STAGE(PG8_SA(0, 1), a2 + hstep, voffA);
;       PG8_WAIT_L(8); PG8_BAR; PG8_WAIT_L(0); PG8_MMA(0, 0, At, B0); PG8_BAR; PG8_SCHED;
;       PG8_LDB(B1, 1, 1); PG8_STAGE(PG8_SB(1, 0), b3, voffB);
;       PG8_BAR; PG8_WAIT_L(0); PG8_MMA(0, 1, At, B1); PG8_BAR;
;       PG8_LDA(At, 1, 1); PG8_STAGE(PG8_SA(1, 0), a3, voffA);
;       PG8_BAR; PG8_WAIT_L(0); PG8_MMA(1, 0, At, B0); PG8_BAR; PG8_SCHED;
;       PG8_STAGE(PG8_SB(1, 1), b3 + hstep, voffB);
;       PG8_WAIT_V(6); PG8_BAR; PG8_MMA(1, 1, At, B1); PG8_BAR;
.LBB0_511:
	ds_read_b128 v[140:143], v146
	ds_read_b128 v[148:151], v146 offset:1024
	ds_read_b128 v[152:155], v146 offset:2048
	ds_read_b128 v[156:159], v146 offset:3072
	s_add_u32 s0, s28, 0xfffc0080
	s_addc_u32 s1, s29, -1
	s_cmp_eq_u32 s60, 12
	s_cselect_b32 s31, s22, s1
	s_cselect_b32 s30, s23, s0
	s_cselect_b32 s1, s27, s59
	s_cselect_b32 s0, s39, s58
	s_add_i32 m0, s6, 0xc000
	ds_read_b128 v[166:169], v145
	ds_read_b128 v[170:173], v145 offset:1024
	ds_read_b128 v[174:177], v145 offset:2048
	ds_read_b128 v[178:181], v145 offset:3072
	ds_read_b128 v[182:185], v145 offset:4096
	ds_read_b128 v[186:189], v145 offset:5120
	ds_read_b128 v[190:193], v145 offset:6144
	ds_read_b128 v[194:197], v145 offset:7168
	global_load_lds_dwordx4 v136, s[28:29]
	s_add_i32 m0, s6, 0xe000
	s_nop 0
	global_load_lds_dwordx4 v138, s[28:29]
	s_barrier
	s_waitcnt lgkmcnt(0)
	v_mfma_f32_16x16x32_bf16 v[118:121], v[140:143], v[166:169], v[118:121]
	v_mfma_f32_16x16x32_bf16 v[110:113], v[152:155], v[166:169], v[110:113]
	v_mfma_f32_16x16x32_bf16 v[90:93], v[140:143], v[174:177], v[90:93]
	v_mfma_f32_16x16x32_bf16 v[82:85], v[152:155], v[174:177], v[82:85]
	v_mfma_f32_16x16x32_bf16 v[62:65], v[140:143], v[182:185], v[62:65]
	v_mfma_f32_16x16x32_bf16 v[50:53], v[152:155], v[182:185], v[50:53]
	v_mfma_f32_16x16x32_bf16 v[42:45], v[140:143], v[190:193], v[42:45]
	v_mfma_f32_16x16x32_bf16 v[22:25], v[152:155], v[190:193], v[22:25]
	v_mfma_f32_16x16x32_bf16 v[118:121], v[148:151], v[170:173], v[118:121]
	v_mfma_f32_16x16x32_bf16 v[110:113], v[156:159], v[170:173], v[110:113]
	v_mfma_f32_16x16x32_bf16 v[90:93], v[148:151], v[178:181], v[90:93]
	v_mfma_f32_16x16x32_bf16 v[82:85], v[156:159], v[178:181], v[82:85]
	v_mfma_f32_16x16x32_bf16 v[62:65], v[148:151], v[186:189], v[62:65]
	v_mfma_f32_16x16x32_bf16 v[50:53], v[156:159], v[186:189], v[50:53]
	v_mfma_f32_16x16x32_bf16 v[42:45], v[148:151], v[194:197], v[42:45]
	v_mfma_f32_16x16x32_bf16 v[22:25], v[156:159], v[194:197], v[22:25]
	s_barrier
	ds_read_b128 v[198:201], v146 offset:16384
	ds_read_b128 v[202:205], v146 offset:17408
	s_mov_b32 m0, s7
	ds_read_b128 v[206:209], v146 offset:18432
	ds_read_b128 v[210:213], v146 offset:19456
	global_load_lds_dwordx4 v0, s[0:1]
	s_mov_b32 m0, s12
	s_nop 0
	global_load_lds_dwordx4 v130, s[0:1]
	s_barrier
	s_waitcnt lgkmcnt(0)
	v_mfma_f32_16x16x32_bf16 v[122:125], v[198:201], v[166:169], v[122:125]
	v_mfma_f32_16x16x32_bf16 v[126:129], v[206:209], v[166:169], v[126:129]
	v_mfma_f32_16x16x32_bf16 v[102:105], v[198:201], v[174:177], v[102:105]
	v_mfma_f32_16x16x32_bf16 v[114:117], v[206:209], v[174:177], v[114:117]
	v_mfma_f32_16x16x32_bf16 v[86:89], v[198:201], v[182:185], v[86:89]
	v_mfma_f32_16x16x32_bf16 v[98:101], v[206:209], v[182:185], v[98:101]
	v_mfma_f32_16x16x32_bf16 v[58:61], v[198:201], v[190:193], v[58:61]
	v_mfma_f32_16x16x32_bf16 v[74:77], v[206:209], v[190:193], v[74:77]
	v_mfma_f32_16x16x32_bf16 v[122:125], v[202:205], v[170:173], v[122:125]
	v_mfma_f32_16x16x32_bf16 v[126:129], v[210:213], v[170:173], v[126:129]
	v_mfma_f32_16x16x32_bf16 v[102:105], v[202:205], v[178:181], v[102:105]
	v_mfma_f32_16x16x32_bf16 v[114:117], v[210:213], v[178:181], v[114:117]
	v_mfma_f32_16x16x32_bf16 v[86:89], v[202:205], v[186:189], v[86:89]
	v_mfma_f32_16x16x32_bf16 v[98:101], v[210:213], v[186:189], v[98:101]
	v_mfma_f32_16x16x32_bf16 v[58:61], v[202:205], v[194:197], v[58:61]
	v_mfma_f32_16x16x32_bf16 v[74:77], v[210:213], v[194:197], v[74:77]
	s_mov_b32 m0, s6
	s_barrier
	ds_read_b128 v[166:169], v145 offset:16384
	ds_read_b128 v[170:173], v145 offset:17408
	ds_read_b128 v[174:177], v145 offset:18432
	ds_read_b128 v[178:181], v145 offset:19456
	ds_read_b128 v[182:185], v145 offset:20480
	ds_read_b128 v[186:189], v145 offset:21504
	ds_read_b128 v[190:193], v145 offset:22528
	ds_read_b128 v[194:197], v145 offset:23552
	global_load_lds_dwordx4 v134, s[30:31]
	s_mov_b32 m0, s13
	s_nop 0
	global_load_lds_dwordx4 v132, s[30:31]
	s_barrier
	s_waitcnt lgkmcnt(0)
	v_mfma_f32_16x16x32_bf16 v[38:41], v[140:143], v[166:169], v[38:41]
	v_mfma_f32_16x16x32_bf16 v[18:21], v[152:155], v[166:169], v[18:21]
	v_mfma_f32_16x16x32_bf16 v[10:13], v[140:143], v[174:177], v[10:13]
	v_mfma_f32_16x16x32_bf16 v[2:5], v[152:155], v[174:177], v[2:5]
	v_mfma_f32_16x16x32_bf16 v[46:49], v[140:143], v[182:185], v[46:49]
	v_mfma_f32_16x16x32_bf16 v[30:33], v[152:155], v[182:185], v[30:33]
	v_mfma_f32_16x16x32_bf16 v[14:17], v[140:143], v[190:193], v[14:17]
	v_mfma_f32_16x16x32_bf16 v[6:9], v[152:155], v[190:193], v[6:9]
	v_mfma_f32_16x16x32_bf16 v[38:41], v[148:151], v[170:173], v[38:41]
	v_mfma_f32_16x16x32_bf16 v[18:21], v[156:159], v[170:173], v[18:21]
	v_mfma_f32_16x16x32_bf16 v[10:13], v[148:151], v[178:181], v[10:13]
	v_mfma_f32_16x16x32_bf16 v[2:5], v[156:159], v[178:181], v[2:5]
	v_mfma_f32_16x16x32_bf16 v[46:49], v[148:151], v[186:189], v[46:49]
	v_mfma_f32_16x16x32_bf16 v[30:33], v[156:159], v[186:189], v[30:33]
	v_mfma_f32_16x16x32_bf16 v[14:17], v[148:151], v[194:197], v[14:17]
	v_mfma_f32_16x16x32_bf16 v[6:9], v[156:159], v[194:197], v[6:9]
	s_barrier
	s_add_u32 s80, s0, 0x40000
	s_addc_u32 s81, s1, 0
	s_mov_b32 m0, s14
	s_nop 0
	global_load_lds_dwordx4 v0, s[80:81]
	s_mov_b32 m0, s15
	s_nop 0
	global_load_lds_dwordx4 v130, s[80:81]
	s_waitcnt vmcnt(6)
	s_barrier
; #define PG8_STAGE(bufoff, gbase, voff) do { _Pragma("unroll") for (int _i = 0; _i < 2; ++_i) \
;     __builtin_amdgcn_global_load_lds((const unsigned*)((const char*)(gbase) + (voff)[_i]), (PG8_LAS unsigned*)(lds + (bufoff) + ldsw + _i * 8192), 16, 0, 0); } while (0)
; #define PG8_LDA(dst, b, h) do { _Pragma("unroll") for (int m = 0; m < 4; ++m) _Pragma("unroll") for (int k = 0; k < 2; ++k) dst[m][k] = *(const PG8_LAS bf16x8*)(lds + PG8_SA(b, h) + aoff + m * 2048 + k * 1024); } while (0)
; #define PG8_LDB(dst, b, h) do { _Pragma("unroll") for (int n = 0; n < 2; ++n) _Pragma("unroll") for (int k = 0; k < 2; ++k) dst[n][k] = *(const PG8_LAS bf16x8*)(lds + PG8_SB(b, h) + boff + n * 2048 + k * 1024); } while (0)
; template <class Epi>
; DI void gemm_phase(const bf16_t* __restrict__ gA, const bf16_t* __restrict__ gBt, int M, int N, int K, const Epi& E, char* lds_generic) {
;     ...
;     for (int t = 0; t < nt; t += 2) {
;       const bool last = (t == nt - 2);
;       const char* a1 = cA + (size_t)(t + 1) * kstep;
;       const char* a2 = last ? nA : cA + (size_t)(t + 2) * kstep; const char* b2 = last ? nB : cB + (size_t)(t + 2) * kstep;
;       const char* a3 = a2 + kstep; const char* b3 = b2 + kstep;
;       PG8_LDB(B0, 0, 0); PG8_SCHED; PG8_LDA(At, 0, 0); PG8_STAGE(PG8_SA(1, 1), a1 + hstep, voffA);
;       PG8_WAIT_L(8); PG8_BAR; PG8_WAIT_L(0); PG8_MMA(0, 0, At, B0); PG8_BAR; PG8_SCHED;
;       PG8_LDB(B1, 0, 1); PG8_STAGE(PG8_SB(0, 0), b2, voffB);
;       PG8_BAR; PG8_WAIT_L(0); PG8_MMA(0, 1, At, B1); PG8_BAR;
;       PG8_LDA(At, 0, 1); PG8_STAGE(PG8_SA(0, 0), a2, voffA);
;       PG8_BAR; PG8_WAIT_L(0); PG8_MMA(1, 0, At, B0); PG8_BAR; PG8_SCHED;
;       PG8_STAGE(PG8_SB(0, 1), b2 + hstep, voffB);
;       PG8_WAIT_V(6); PG8_BAR; PG8_MMA(1, 1, At, B1); PG8_BAR;
;       PG8_LDB(B0, 1, 0); PG8_SCHED; PG8_LDA(At, 1, 0); PG8_STAGE(PG8_SA(0, 1), a2 + hstep, voffA);
;       PG8_WAIT_L(8); PG8_BAR; PG8_WAIT_L(0); PG8_MMA(0, 0, At, B0); PG8_BAR; PG8_SCHED;
;       PG8_LDB(B1, 1, 1); PG8_STAGE(PG8_SB(1, 0), b3, voffB);
;       PG8_BAR; PG8_WAIT_L(0); PG8_MMA(0, 1, At, B1); PG8_BAR;
;       PG8_LDA(At, 1, 1); PG8_STAGE(PG8_SA(1, 0), a3, voffA);
;       PG8_BAR; PG8_WAIT_L(0); PG8_MMA(1, 0, At, B0); PG8_BAR; PG8_SCHED;
;       PG8_STAGE(PG8_SB(1, 1), b3 + hstep, voffB);
;       PG8_WAIT_V(6); PG8_BAR; PG8_MMA(1, 1, At, B1); PG8_BAR;
	v_mfma_f32_16x16x32_bf16 v[54:57], v[198:201], v[166:169], v[54:57]
	v_mfma_f32_16x16x32_bf16 v[66:69], v[206:209], v[166:169], v[66:69]
	v_mfma_f32_16x16x32_bf16 v[94:97], v[198:201], v[174:177], v[94:97]
	v_mfma_f32_16x16x32_bf16 v[106:109], v[206:209], v[174:177], v[106:109]
	v_mfma_f32_16x16x32_bf16 v[70:73], v[198:201], v[182:185], v[70:73]
	v_mfma_f32_16x16x32_bf16 v[78:81], v[206:209], v[182:185], v[78:81]
	v_mfma_f32_16x16x32_bf16 v[26:29], v[198:201], v[190:193], v[26:29]
	v_mfma_f32_16x16x32_bf16 v[34:37], v[206:209], v[190:193], v[34:37]
	v_mfma_f32_16x16x32_bf16 v[54:57], v[202:205], v[170:173], v[54:57]
	v_mfma_f32_16x16x32_bf16 v[66:69], v[210:213], v[170:173], v[66:69]
	v_mfma_f32_16x16x32_bf16 v[94:97], v[202:205], v[178:181], v[94:97]
	v_mfma_f32_16x16x32_bf16 v[106:109], v[210:213], v[178:181], v[106:109]
	v_mfma_f32_16x16x32_bf16 v[70:73], v[202:205], v[186:189], v[70:73]
	v_mfma_f32_16x16x32_bf16 v[78:81], v[210:213], v[186:189], v[78:81]
	v_mfma_f32_16x16x32_bf16 v[26:29], v[202:205], v[194:197], v[26:29]
	v_mfma_f32_16x16x32_bf16 v[34:37], v[210:213], v[194:197], v[34:37]
	s_barrier
	ds_read_b128 v[140:143], v146 offset:32768
	ds_read_b128 v[148:151], v146 offset:33792
	ds_read_b128 v[152:155], v146 offset:34816
	ds_read_b128 v[156:159], v146 offset:35840
	s_add_u32 s30, s30, 0x40000
	s_addc_u32 s31, s31, 0
	s_mov_b32 m0, s16
	ds_read_b128 v[166:169], v145 offset:32768
	ds_read_b128 v[170:173], v145 offset:33792
	ds_read_b128 v[174:177], v145 offset:34816
	ds_read_b128 v[178:181], v145 offset:35840
	ds_read_b128 v[182:185], v145 offset:36864
	ds_read_b128 v[186:189], v145 offset:37888
	ds_read_b128 v[190:193], v145 offset:38912
	ds_read_b128 v[194:197], v145 offset:39936
	global_load_lds_dwordx4 v134, s[30:31]
	s_mov_b32 m0, s18
	s_nop 0
	global_load_lds_dwordx4 v132, s[30:31]
	s_barrier
	s_waitcnt lgkmcnt(0)
	s_waitcnt lgkmcnt(0)
	v_mfma_f32_16x16x32_bf16 v[118:121], v[140:143], v[166:169], v[118:121]
	v_mfma_f32_16x16x32_bf16 v[110:113], v[152:155], v[166:169], v[110:113]
	v_mfma_f32_16x16x32_bf16 v[90:93], v[140:143], v[174:177], v[90:93]
	v_mfma_f32_16x16x32_bf16 v[82:85], v[152:155], v[174:177], v[82:85]
	v_mfma_f32_16x16x32_bf16 v[62:65], v[140:143], v[182:185], v[62:65]
	v_mfma_f32_16x16x32_bf16 v[50:53], v[152:155], v[182:185], v[50:53]
	v_mfma_f32_16x16x32_bf16 v[42:45], v[140:143], v[190:193], v[42:45]
	v_mfma_f32_16x16x32_bf16 v[22:25], v[152:155], v[190:193], v[22:25]
	v_mfma_f32_16x16x32_bf16 v[118:121], v[148:151], v[170:173], v[118:121]
	v_mfma_f32_16x16x32_bf16 v[110:113], v[156:159], v[170:173], v[110:113]
	v_mfma_f32_16x16x32_bf16 v[90:93], v[148:151], v[178:181], v[90:93]
	v_mfma_f32_16x16x32_bf16 v[82:85], v[156:159], v[178:181], v[82:85]
	v_mfma_f32_16x16x32_bf16 v[62:65], v[148:151], v[186:189], v[62:65]
	v_mfma_f32_16x16x32_bf16 v[50:53], v[156:159], v[186:189], v[50:53]
	v_mfma_f32_16x16x32_bf16 v[42:45], v[148:151], v[194:197], v[42:45]
	v_mfma_f32_16x16x32_bf16 v[22:25], v[156:159], v[194:197], v[22:25]
	s_barrier
	s_mov_b32 m0, s8
	ds_read_b128 v[198:201], v146 offset:49152
	ds_read_b128 v[202:205], v146 offset:50176
	ds_read_b128 v[206:209], v146 offset:51200
	ds_read_b128 v[210:213], v146 offset:52224
	s_add_u32 s80, s0, 0x80
	s_addc_u32 s81, s1, 0
	global_load_lds_dwordx4 v0, s[80:81]
	s_mov_b32 m0, s9
	s_nop 0
	s_add_u32 s80, s0, 0x80
	s_addc_u32 s81, s1, 0
	global_load_lds_dwordx4 v130, s[80:81]
	s_barrier
	s_waitcnt lgkmcnt(0)
	v_mfma_f32_16x16x32_bf16 v[122:125], v[198:201], v[166:169], v[122:125]
	v_mfma_f32_16x16x32_bf16 v[126:129], v[206:209], v[166:169], v[126:129]
	v_mfma_f32_16x16x32_bf16 v[102:105], v[198:201], v[174:177], v[102:105]
	v_mfma_f32_16x16x32_bf16 v[114:117], v[206:209], v[174:177], v[114:117]
	v_mfma_f32_16x16x32_bf16 v[86:89], v[198:201], v[182:185], v[86:89]
	v_mfma_f32_16x16x32_bf16 v[98:101], v[206:209], v[182:185], v[98:101]
	v_mfma_f32_16x16x32_bf16 v[58:61], v[198:201], v[190:193], v[58:61]
	v_mfma_f32_16x16x32_bf16 v[74:77], v[206:209], v[190:193], v[74:77]
	v_mfma_f32_16x16x32_bf16 v[122:125], v[202:205], v[170:173], v[122:125]
	v_mfma_f32_16x16x32_bf16 v[126:129], v[210:213], v[170:173], v[126:129]
	v_mfma_f32_16x16x32_bf16 v[102:105], v[202:205], v[178:181], v[102:105]
	v_mfma_f32_16x16x32_bf16 v[114:117], v[210:213], v[178:181], v[114:117]
	v_mfma_f32_16x16x32_bf16 v[86:89], v[202:205], v[186:189], v[86:89]
	v_mfma_f32_16x16x32_bf16 v[98:101], v[210:213], v[186:189], v[98:101]
	v_mfma_f32_16x16x32_bf16 v[58:61], v[202:205], v[194:197], v[58:61]
	v_mfma_f32_16x16x32_bf16 v[74:77], v[210:213], v[194:197], v[74:77]
	s_mov_b32 m0, s19
	s_barrier
; #define PG8_LAS __attribute__((address_space(3)))
;   DI void init(f32x4 (&acc)[2][2][4][2], const Unit& u, int wr, int wc, int fr, int fq) const {
;     const int row0 = u.pm * BM + wr * 64 + fr, col0 = u.pn * BM + wc * 32 + 8 * fq; const float ic = 1.f / coef;
; #pragma unroll
;     for (int ai = 0; ai < 2; ++ai)
; #pragma unroll
;       for (int m = 0; m < 4; ++m) { const bf16_t* rowp = src + (size_t)(row0 + ai * HALF + m * 16) * DM + col0;
; #pragma unroll
; template <class Epi>
; DI void gemm_phase(const bf16_t* __restrict__ gA, const bf16_t* __restrict__ gBt, int M, int N, int K, const Epi& E, char* lds_generic) {
;     ...
;     for (int t = 0; t < nt; t += 2) {
;       const bool last = (t == nt - 2);
;       const char* a1 = cA + (size_t)(t + 1) * kstep;
;       const char* a2 = last ? nA : cA + (size_t)(t + 2) * kstep; const char* b2 = last ? nB : cB + (size_t)(t + 2) * kstep;
;       const char* a3 = a2 + kstep; const char* b3 = b2 + kstep;
;       PG8_LDB(B0, 0, 0); PG8_SCHED; PG8_LDA(At, 0, 0); PG8_STAGE(PG8_SA(1, 1), a1 + hstep, voffA);
;       PG8_WAIT_L(8); PG8_BAR; PG8_WAIT_L(0); PG8_MMA(0, 0, At, B0); PG8_BAR; PG8_SCHED;
;       PG8_LDB(B1, 0, 1); PG8_STAGE(PG8_SB(0, 0), b2, voffB);
;       PG8_BAR; PG8_WAIT_L(0); PG8_MMA(0, 1, At, B1); PG8_BAR;
;       PG8_LDA(At, 0, 1); PG8_STAGE(PG8_SA(0, 0), a2, voffA);
;       PG8_BAR; PG8_WAIT_L(0); PG8_MMA(1, 0, At, B0); PG8_BAR; PG8_SCHED;
;       PG8_STAGE(PG8_SB(0, 1), b2 + hstep, voffB);
;       PG8_WAIT_V(6); PG8_BAR; PG8_MMA(1, 1, At, B1); PG8_BAR;
;       PG8_LDB(B0, 1, 0); PG8_SCHED; PG8_LDA(At, 1, 0); PG8_STAGE(PG8_SA(0, 1), a2 + hstep, voffA);
;       PG8_WAIT_L(8); PG8_BAR; PG8_WAIT_L(0); PG8_MMA(0, 0, At, B0); PG8_BAR; PG8_SCHED;
;       PG8_LDB(B1, 1, 1); PG8_STAGE(PG8_SB(1, 0), b3, voffB);
;       PG8_BAR; PG8_WAIT_L(0); PG8_MMA(0, 1, At, B1); PG8_BAR;
;       PG8_LDA(At, 1, 1); PG8_STAGE(PG8_SA(1, 0), a3, voffA);
;       PG8_BAR; PG8_WAIT_L(0); PG8_MMA(1, 0, At, B0); PG8_BAR; PG8_SCHED;
;       PG8_STAGE(PG8_SB(1, 1), b3 + hstep, voffB);
;       PG8_WAIT_V(6); PG8_BAR; PG8_MMA(1, 1, At, B1); PG8_BAR;
;     }
;     uint4 rtn_ = {0u, 0u, 0u, 0u};
;     if (has_next) PG8_RTAB_LOAD(rtn_, nxt);
;     E(acc, cur, wr, wc, fr, fq, (const PG8_LAS float*)(lds + RT_OFF) + (ui & 1) * 256);
;     if (!has_next) break;
;     PG8_RTAB_FIN(rtn_, (ui + 1) & 1);
;     E.init(acc, nxt, wr, wc, fr, fq);
	ds_read_b128 v[166:169], v145 offset:49152
	ds_read_b128 v[170:173], v145 offset:50176
	ds_read_b128 v[174:177], v145 offset:51200
	ds_read_b128 v[178:181], v145 offset:52224
	ds_read_b128 v[182:185], v145 offset:53248
	ds_read_b128 v[186:189], v145 offset:54272
	ds_read_b128 v[190:193], v145 offset:55296
	ds_read_b128 v[194:197], v145 offset:56320
	s_add_u32 s80, s30, 0xfffc0080
	s_addc_u32 s81, s31, -1
	global_load_lds_dwordx4 v134, s[80:81]
	s_mov_b32 m0, s33
	s_nop 0
	s_add_u32 s80, s30, 0xfffc0080
	s_addc_u32 s81, s31, -1
	global_load_lds_dwordx4 v132, s[80:81]
	s_barrier
	s_waitcnt lgkmcnt(0)
	v_mfma_f32_16x16x32_bf16 v[38:41], v[140:143], v[166:169], v[38:41]
	v_mfma_f32_16x16x32_bf16 v[18:21], v[152:155], v[166:169], v[18:21]
	v_mfma_f32_16x16x32_bf16 v[10:13], v[140:143], v[174:177], v[10:13]
	v_mfma_f32_16x16x32_bf16 v[2:5], v[152:155], v[174:177], v[2:5]
	v_mfma_f32_16x16x32_bf16 v[46:49], v[140:143], v[182:185], v[46:49]
	v_mfma_f32_16x16x32_bf16 v[30:33], v[152:155], v[182:185], v[30:33]
	v_mfma_f32_16x16x32_bf16 v[14:17], v[140:143], v[190:193], v[14:17]
	v_mfma_f32_16x16x32_bf16 v[6:9], v[152:155], v[190:193], v[6:9]
	v_mfma_f32_16x16x32_bf16 v[38:41], v[148:151], v[170:173], v[38:41]
	v_mfma_f32_16x16x32_bf16 v[18:21], v[156:159], v[170:173], v[18:21]
	v_mfma_f32_16x16x32_bf16 v[10:13], v[148:151], v[178:181], v[10:13]
	v_mfma_f32_16x16x32_bf16 v[2:5], v[156:159], v[178:181], v[2:5]
	v_mfma_f32_16x16x32_bf16 v[46:49], v[148:151], v[186:189], v[46:49]
	v_mfma_f32_16x16x32_bf16 v[30:33], v[156:159], v[186:189], v[30:33]
	v_mfma_f32_16x16x32_bf16 v[14:17], v[148:151], v[194:197], v[14:17]
	v_mfma_f32_16x16x32_bf16 v[6:9], v[156:159], v[194:197], v[6:9]
	s_barrier
	s_add_u32 s0, s0, 0x40080
	s_addc_u32 s1, s1, 0
	s_mov_b32 m0, s35
	s_nop 0
	global_load_lds_dwordx4 v0, s[0:1]
	s_mov_b32 m0, s42
	s_nop 0
	global_load_lds_dwordx4 v130, s[0:1]
	s_waitcnt vmcnt(6)
	s_barrier
	v_mfma_f32_16x16x32_bf16 v[54:57], v[198:201], v[166:169], v[54:57]
	v_mfma_f32_16x16x32_bf16 v[66:69], v[206:209], v[166:169], v[66:69]
	v_mfma_f32_16x16x32_bf16 v[94:97], v[198:201], v[174:177], v[94:97]
	v_mfma_f32_16x16x32_bf16 v[106:109], v[206:209], v[174:177], v[106:109]
	v_mfma_f32_16x16x32_bf16 v[70:73], v[198:201], v[182:185], v[70:73]
	v_mfma_f32_16x16x32_bf16 v[78:81], v[206:209], v[182:185], v[78:81]
	v_mfma_f32_16x16x32_bf16 v[26:29], v[198:201], v[190:193], v[26:29]
	v_mfma_f32_16x16x32_bf16 v[34:37], v[206:209], v[190:193], v[34:37]
	v_mfma_f32_16x16x32_bf16 v[54:57], v[202:205], v[170:173], v[54:57]
	v_mfma_f32_16x16x32_bf16 v[66:69], v[210:213], v[170:173], v[66:69]
	v_mfma_f32_16x16x32_bf16 v[94:97], v[202:205], v[178:181], v[94:97]
	v_mfma_f32_16x16x32_bf16 v[106:109], v[210:213], v[178:181], v[106:109]
	v_mfma_f32_16x16x32_bf16 v[70:73], v[202:205], v[186:189], v[70:73]
	v_mfma_f32_16x16x32_bf16 v[78:81], v[210:213], v[186:189], v[78:81]
	v_mfma_f32_16x16x32_bf16 v[26:29], v[202:205], v[194:197], v[26:29]
	v_mfma_f32_16x16x32_bf16 v[34:37], v[210:213], v[194:197], v[34:37]
	s_add_i32 s60, s60, 2
	s_add_u32 s28, s28, 0x100
	s_addc_u32 s29, s29, 0
	s_add_u32 s58, s58, 0x100
	s_addc_u32 s59, s59, 0
	s_cmp_gt_u32 s60, 13
	s_barrier
	s_cbranch_scc0 .LBB0_511
	s_cmp_eq_u64 vcc, 0
	s_cbranch_scc1 .Leinit511_skip
	v_lshl_add_u32 v246, s38, 8, v144
	v_lshl_or_b32 v247, s26, 8, v147
	v_lshlrev_b32_e32 v246, 11, v246
	v_lshl_add_u32 v246, v247, 1, v246
	global_load_dwordx4 v[166:169], v246, s[92:93]
	global_load_dwordx4 v[170:173], v246, s[92:93] offset:256
	s_add_u32 s80, s92, 0x8000
	s_addc_u32 s81, s93, 0
	global_load_dwordx4 v[174:177], v246, s[80:81]
	global_load_dwordx4 v[178:181], v246, s[80:81] offset:256
	s_add_u32 s80, s92, 0x10000
	s_addc_u32 s81, s93, 0
	global_load_dwordx4 v[182:185], v246, s[80:81]
	global_load_dwordx4 v[186:189], v246, s[80:81] offset:256
	s_add_u32 s80, s92, 0x18000
	s_addc_u32 s81, s93, 0
	global_load_dwordx4 v[190:193], v246, s[80:81]
	global_load_dwordx4 v[198:201], v246, s[80:81] offset:256
	s_add_u32 s80, s92, 0x40000
	s_addc_u32 s81, s93, 0
	global_load_dwordx4 v[194:197], v246, s[80:81]
	global_load_dwordx4 v[202:205], v246, s[80:81] offset:256
	s_add_u32 s80, s92, 0x48000
	s_addc_u32 s81, s93, 0
	global_load_dwordx4 v[206:209], v246, s[80:81]
	global_load_dwordx4 v[210:213], v246, s[80:81] offset:256
	s_add_u32 s80, s92, 0x50000
	s_addc_u32 s81, s93, 0
	global_load_dwordx4 v[214:217], v246, s[80:81]
	global_load_dwordx4 v[218:221], v246, s[80:81] offset:256
	s_add_u32 s80, s92, 0x58000
	s_addc_u32 s81, s93, 0
	global_load_dwordx4 v[238:241], v246, s[80:81]
	global_load_dwordx4 v[242:245], v246, s[80:81] offset:256

; #define PG8_STAGE(bufoff, gbase, voff) do { _Pragma("unroll") for (int _i = 0; _i < 2; ++_i) \
;     __builtin_amdgcn_global_load_lds((const unsigned*)((const char*)(gbase) + (voff)[_i]), (PG8_LAS unsigned*)(lds + (bufoff) + ldsw + _i * 8192), 16, 0, 0); } while (0)
; #define PG8_WAIT_V(n) asm volatile("s_waitcnt vmcnt(" #n ")" ::: "memory")
; #define PG8_WAIT_L(n) asm volatile("s_waitcnt lgkmcnt(" #n ")" ::: "memory")
; DI void acc_zero(f32x4 (&acc)[2][2][4][2]) {
; #pragma unroll
;   for (int a = 0; a < 2; ++a)
; #pragma unroll
;     for (int b = 0; b < 2; ++b)
; #pragma unroll
;       for (int m = 0; m < 4; ++m)
; #pragma unroll
;         for (int n = 0; n < 2; ++n) acc[a][b][m][n] = (f32x4){0.f, 0.f, 0.f, 0.f};
; template <class Epi>
; DI void gemm_phase(const bf16_t* __restrict__ gA, const bf16_t* __restrict__ gBt, int M, int N, int K, const Epi& E, char* lds_generic) {
;     ...
;     for (int t = 0; t < nt; t += 2) {
;       const bool last = (t == nt - 2);
;       const char* a1 = cA + (size_t)(t + 1) * kstep;
;       const char* a2 = last ? nA : cA + (size_t)(t + 2) * kstep; const char* b2 = last ? nB : cB + (size_t)(t + 2) * kstep;
;       const char* a3 = a2 + kstep; const char* b3 = b2 + kstep;
;       PG8_LDB(B0, 0, 0); PG8_SCHED; PG8_LDA(At, 0, 0); PG8_STAGE(PG8_SA(1, 1), a1 + hstep, voffA);
;       PG8_WAIT_L(8); PG8_BAR; PG8_WAIT_L(0); PG8_MMA(0, 0, At, B0); PG8_BAR; PG8_SCHED;
;       PG8_LDB(B1, 0, 1); PG8_STAGE(PG8_SB(0, 0), b2, voffB);
;       PG8_BAR; PG8_WAIT_L(0); PG8_MMA(0, 1, At, B1); PG8_BAR;
;       PG8_LDA(At, 0, 1); PG8_STAGE(PG8_SA(0, 0), a2, voffA);
;       PG8_BAR; PG8_WAIT_L(0); PG8_MMA(1, 0, At, B0); PG8_BAR; PG8_SCHED;
;       PG8_STAGE(PG8_SB(0, 1), b2 + hstep, voffB);
;       PG8_WAIT_V(6); PG8_BAR; PG8_MMA(1, 1, At, B1); PG8_BAR;
;       PG8_LDB(B0, 1, 0); PG8_SCHED; PG8_LDA(At, 1, 0); PG8_STAGE(PG8_SA(0, 1), a2 + hstep, voffA);
;       PG8_WAIT_L(8); PG8_BAR; PG8_WAIT_L(0); PG8_MMA(0, 0, At, B0); PG8_BAR; PG8_SCHED;
;       PG8_LDB(B1, 1, 1); PG8_STAGE(PG8_SB(1, 0), b3, voffB);
;       PG8_BAR; PG8_WAIT_L(0); PG8_MMA(0, 1, At, B1); PG8_BAR;
;       PG8_LDA(At, 1, 1); PG8_STAGE(PG8_SA(1, 0), a3, voffA);
;       PG8_BAR; PG8_WAIT_L(0); PG8_MMA(1, 0, At, B0); PG8_BAR; PG8_SCHED;
;       PG8_STAGE(PG8_SB(1, 1), b3 + hstep, voffB);
;       PG8_WAIT_V(6); PG8_BAR; PG8_MMA(1, 1, At, B1); PG8_BAR;
.LBB0_604:
	s_ashr_i32 s87, s86, 31
	s_lshl_b64 s[20:21], s[86:87], 19
	s_add_u32 s88, s82, s20
	s_addc_u32 s89, s83, s21
	s_and_b64 s[20:21], s[38:39], exec
	s_cselect_b32 s20, s89, s29
	s_cselect_b32 s21, s88, s28
	s_ashr_i32 s27, s26, 31
	s_lshl_b64 s[22:23], s[26:27], 19
	s_add_u32 s90, s16, s22
	s_addc_u32 s91, s4, s23
	s_and_b64 s[22:23], s[38:39], exec
	s_cselect_b32 s27, s91, s31
	s_cselect_b32 s42, s90, s30
	s_add_u32 vcc_lo, s28, 0x40080
	s_addc_u32 vcc_hi, s29, 0
	s_add_u32 s87, s30, 0x100
	s_addc_u32 s22, s31, 0
	s_mov_b32 s23, -2
	ds_read_b128 v[50:53], v155
	ds_read_b128 v[146:149], v155 offset:1024
	ds_read_b128 v[158:161], v155 offset:2048
	ds_read_b128 v[166:169], v155 offset:3072
	s_add_u32 s24, vcc_lo, 0xfffc0080
	s_addc_u32 s25, vcc_hi, -1
	s_cmp_eq_u32 s23, 12
	s_cselect_b32 s31, s20, s25
	s_cselect_b32 s30, s21, s24
	s_cselect_b32 s29, s27, s22
	s_cselect_b32 s28, s42, s87
	s_add_i32 m0, s72, 0xc000
	ds_read_b128 v[170:173], v154
	ds_read_b128 v[174:177], v154 offset:1024
	ds_read_b128 v[178:181], v154 offset:2048
	ds_read_b128 v[182:185], v154 offset:3072
	ds_read_b128 v[186:189], v154 offset:4096
	ds_read_b128 v[190:193], v154 offset:5120
	ds_read_b128 v[194:197], v154 offset:6144
	ds_read_b128 v[198:201], v154 offset:7168
	global_load_lds_dwordx4 v142, vcc
	s_add_i32 m0, s72, 0xe000
	s_nop 0
	global_load_lds_dwordx4 v144, vcc
	s_barrier
	s_waitcnt lgkmcnt(0)
	s_waitcnt lgkmcnt(0)
	v_mfma_f32_16x16x32_bf16 v[130:133], v[50:53], v[170:173], 0
	v_mfma_f32_16x16x32_bf16 v[122:125], v[158:161], v[170:173], 0
	v_mfma_f32_16x16x32_bf16 v[114:117], v[50:53], v[178:181], 0
	v_mfma_f32_16x16x32_bf16 v[106:109], v[158:161], v[178:181], 0
	v_mfma_f32_16x16x32_bf16 v[98:101], v[50:53], v[186:189], 0
	v_mfma_f32_16x16x32_bf16 v[90:93], v[158:161], v[186:189], 0
	v_mfma_f32_16x16x32_bf16 v[82:85], v[50:53], v[194:197], 0
	v_mfma_f32_16x16x32_bf16 v[74:77], v[158:161], v[194:197], 0
	v_mfma_f32_16x16x32_bf16 v[130:133], v[146:149], v[174:177], v[130:133]
	v_mfma_f32_16x16x32_bf16 v[122:125], v[166:169], v[174:177], v[122:125]
	v_mfma_f32_16x16x32_bf16 v[114:117], v[146:149], v[182:185], v[114:117]
	v_mfma_f32_16x16x32_bf16 v[106:109], v[166:169], v[182:185], v[106:109]
	v_mfma_f32_16x16x32_bf16 v[98:101], v[146:149], v[190:193], v[98:101]
	v_mfma_f32_16x16x32_bf16 v[90:93], v[166:169], v[190:193], v[90:93]
	v_mfma_f32_16x16x32_bf16 v[82:85], v[146:149], v[198:201], v[82:85]
	v_mfma_f32_16x16x32_bf16 v[74:77], v[166:169], v[198:201], v[74:77]
	s_barrier
	s_mov_b32 m0, s14
	ds_read_b128 v[202:205], v155 offset:16384
	ds_read_b128 v[206:209], v155 offset:17408
	ds_read_b128 v[210:213], v155 offset:18432
	ds_read_b128 v[214:217], v155 offset:19456
	global_load_lds_dwordx4 v0, s[28:29]
	s_mov_b32 m0, s15
	s_nop 0
	global_load_lds_dwordx4 v138, s[28:29]
	s_barrier
	s_waitcnt lgkmcnt(0)
	v_mfma_f32_16x16x32_bf16 v[126:129], v[202:205], v[170:173], 0
	v_mfma_f32_16x16x32_bf16 v[118:121], v[210:213], v[170:173], 0
	v_mfma_f32_16x16x32_bf16 v[110:113], v[202:205], v[178:181], 0
	v_mfma_f32_16x16x32_bf16 v[102:105], v[210:213], v[178:181], 0
	v_mfma_f32_16x16x32_bf16 v[94:97], v[202:205], v[186:189], 0
	v_mfma_f32_16x16x32_bf16 v[86:89], v[210:213], v[186:189], 0
	v_mfma_f32_16x16x32_bf16 v[78:81], v[202:205], v[194:197], 0
	v_mfma_f32_16x16x32_bf16 v[70:73], v[210:213], v[194:197], 0
	v_mfma_f32_16x16x32_bf16 v[126:129], v[206:209], v[174:177], v[126:129]
	v_mfma_f32_16x16x32_bf16 v[118:121], v[214:217], v[174:177], v[118:121]
	v_mfma_f32_16x16x32_bf16 v[110:113], v[206:209], v[182:185], v[110:113]
	v_mfma_f32_16x16x32_bf16 v[102:105], v[214:217], v[182:185], v[102:105]
	v_mfma_f32_16x16x32_bf16 v[94:97], v[206:209], v[190:193], v[94:97]
	v_mfma_f32_16x16x32_bf16 v[86:89], v[214:217], v[190:193], v[86:89]
	v_mfma_f32_16x16x32_bf16 v[78:81], v[206:209], v[198:201], v[78:81]
	v_mfma_f32_16x16x32_bf16 v[70:73], v[214:217], v[198:201], v[70:73]
	s_mov_b32 m0, s72
	s_barrier
	ds_read_b128 v[170:173], v154 offset:16384
	ds_read_b128 v[174:177], v154 offset:17408
	ds_read_b128 v[178:181], v154 offset:18432
	ds_read_b128 v[182:185], v154 offset:19456
	ds_read_b128 v[186:189], v154 offset:20480
	ds_read_b128 v[190:193], v154 offset:21504
	ds_read_b128 v[194:197], v154 offset:22528
	ds_read_b128 v[198:201], v154 offset:23552
	global_load_lds_dwordx4 v134, s[30:31]
	s_mov_b32 m0, s58
	s_nop 0
	global_load_lds_dwordx4 v136, s[30:31]
	s_barrier
	s_waitcnt lgkmcnt(0)
	v_mfma_f32_16x16x32_bf16 v[66:69], v[50:53], v[170:173], 0
	v_mfma_f32_16x16x32_bf16 v[58:61], v[158:161], v[170:173], 0
	v_mfma_f32_16x16x32_bf16 v[46:49], v[50:53], v[178:181], 0
	v_mfma_f32_16x16x32_bf16 v[38:41], v[158:161], v[178:181], 0
	v_mfma_f32_16x16x32_bf16 v[30:33], v[50:53], v[186:189], 0
	v_mfma_f32_16x16x32_bf16 v[22:25], v[158:161], v[186:189], 0
	v_mfma_f32_16x16x32_bf16 v[14:17], v[50:53], v[194:197], 0
	v_mfma_f32_16x16x32_bf16 v[6:9], v[158:161], v[194:197], 0
	v_mfma_f32_16x16x32_bf16 v[66:69], v[146:149], v[174:177], v[66:69]
	v_mfma_f32_16x16x32_bf16 v[58:61], v[166:169], v[174:177], v[58:61]
	v_mfma_f32_16x16x32_bf16 v[46:49], v[146:149], v[182:185], v[46:49]
	v_mfma_f32_16x16x32_bf16 v[38:41], v[166:169], v[182:185], v[38:41]
	v_mfma_f32_16x16x32_bf16 v[30:33], v[146:149], v[190:193], v[30:33]
	v_mfma_f32_16x16x32_bf16 v[22:25], v[166:169], v[190:193], v[22:25]
	v_mfma_f32_16x16x32_bf16 v[14:17], v[146:149], v[198:201], v[14:17]
	v_mfma_f32_16x16x32_bf16 v[6:9], v[166:169], v[198:201], v[6:9]
	s_barrier
	s_add_u32 s24, s28, 0x40000
	s_addc_u32 s25, s29, 0
	s_mov_b32 m0, s59
	s_nop 0
	global_load_lds_dwordx4 v0, s[24:25]
	s_mov_b32 m0, s62
	s_nop 0
	global_load_lds_dwordx4 v138, s[24:25]
	s_waitcnt vmcnt(6)
	s_barrier
	v_mfma_f32_16x16x32_bf16 v[54:57], v[210:213], v[170:173], 0
	v_mfma_f32_16x16x32_bf16 v[42:45], v[202:205], v[178:181], 0
	v_mfma_f32_16x16x32_bf16 v[34:37], v[210:213], v[178:181], 0
	v_mfma_f32_16x16x32_bf16 v[26:29], v[202:205], v[186:189], 0
	v_mfma_f32_16x16x32_bf16 v[18:21], v[210:213], v[186:189], 0
	v_mfma_f32_16x16x32_bf16 v[10:13], v[202:205], v[194:197], 0
	v_mfma_f32_16x16x32_bf16 v[2:5], v[210:213], v[194:197], 0
	v_mfma_f32_16x16x32_bf16 v[50:53], v[202:205], v[170:173], 0
	v_mfma_f32_16x16x32_bf16 v[54:57], v[214:217], v[174:177], v[54:57]
	v_mfma_f32_16x16x32_bf16 v[42:45], v[206:209], v[182:185], v[42:45]
	v_mfma_f32_16x16x32_bf16 v[34:37], v[214:217], v[182:185], v[34:37]
	v_mfma_f32_16x16x32_bf16 v[26:29], v[206:209], v[190:193], v[26:29]
	v_mfma_f32_16x16x32_bf16 v[18:21], v[214:217], v[190:193], v[18:21]
	v_mfma_f32_16x16x32_bf16 v[10:13], v[206:209], v[198:201], v[10:13]
	v_mfma_f32_16x16x32_bf16 v[2:5], v[214:217], v[198:201], v[2:5]
	v_mfma_f32_16x16x32_bf16 v[50:53], v[206:209], v[174:177], v[50:53]
	s_barrier
	s_branch .Lup605_p5
; #define PG8_STAGE(bufoff, gbase, voff) do { _Pragma("unroll") for (int _i = 0; _i < 2; ++_i) \
;     __builtin_amdgcn_global_load_lds((const unsigned*)((const char*)(gbase) + (voff)[_i]), (PG8_LAS unsigned*)(lds + (bufoff) + ldsw + _i * 8192), 16, 0, 0); } while (0)
; #define PG8_LDA(dst, b, h) do { _Pragma("unroll") for (int m = 0; m < 4; ++m) _Pragma("unroll") for (int k = 0; k < 2; ++k) dst[m][k] = *(const PG8_LAS bf16x8*)(lds + PG8_SA(b, h) + aoff + m * 2048 + k * 1024); } while (0)
; #define PG8_LDB(dst, b, h) do { _Pragma("unroll") for (int n = 0; n < 2; ++n) _Pragma("unroll") for (int k = 0; k < 2; ++k) dst[n][k] = *(const PG8_LAS bf16x8*)(lds + PG8_SB(b, h) + boff + n * 2048 + k * 1024); } while (0)
; template <class Epi>
; DI void gemm_phase(const bf16_t* __restrict__ gA, const bf16_t* __restrict__ gBt, int M, int N, int K, const Epi& E, char* lds_generic) {
;     ...
;     for (int t = 0; t < nt; t += 2) {
;       const bool last = (t == nt - 2);
;       const char* a1 = cA + (size_t)(t + 1) * kstep;
;       const char* a2 = last ? nA : cA + (size_t)(t + 2) * kstep; const char* b2 = last ? nB : cB + (size_t)(t + 2) * kstep;
;       const char* a3 = a2 + kstep; const char* b3 = b2 + kstep;
;       PG8_LDB(B0, 0, 0); PG8_SCHED; PG8_LDA(At, 0, 0); PG8_STAGE(PG8_SA(1, 1), a1 + hstep, voffA);
;       PG8_WAIT_L(8); PG8_BAR; PG8_WAIT_L(0); PG8_MMA(0, 0, At, B0); PG8_BAR; PG8_SCHED;
;       PG8_LDB(B1, 0, 1); PG8_STAGE(PG8_SB(0, 0), b2, voffB);
;       PG8_BAR; PG8_WAIT_L(0); PG8_MMA(0, 1, At, B1); PG8_BAR;
;       PG8_LDA(At, 0, 1); PG8_STAGE(PG8_SA(0, 0), a2, voffA);
;       PG8_BAR; PG8_WAIT_L(0); PG8_MMA(1, 0, At, B0); PG8_BAR; PG8_SCHED;
;       PG8_STAGE(PG8_SB(0, 1), b2 + hstep, voffB);
;       PG8_WAIT_V(6); PG8_BAR; PG8_MMA(1, 1, At, B1); PG8_BAR;
;       PG8_LDB(B0, 1, 0); PG8_SCHED; PG8_LDA(At, 1, 0); PG8_STAGE(PG8_SA(0, 1), a2 + hstep, voffA);
;       PG8_WAIT_L(8); PG8_BAR; PG8_WAIT_L(0); PG8_MMA(0, 0, At, B0); PG8_BAR; PG8_SCHED;
;       PG8_LDB(B1, 1, 1); PG8_STAGE(PG8_SB(1, 0), b3, voffB);
;       PG8_BAR; PG8_WAIT_L(0); PG8_MMA(0, 1, At, B1); PG8_BAR;
;       PG8_LDA(At, 1, 1); PG8_STAGE(PG8_SA(1, 0), a3, voffA);
;       PG8_BAR; PG8_WAIT_L(0); PG8_MMA(1, 0, At, B0); PG8_BAR; PG8_SCHED;
;       PG8_STAGE(PG8_SB(1, 1), b3 + hstep, voffB);
;       PG8_WAIT_V(6); PG8_BAR; PG8_MMA(1, 1, At, B1); PG8_BAR;
.LBB0_605:
	ds_read_b128 v[50:53], v155
	ds_read_b128 v[146:149], v155 offset:1024
	ds_read_b128 v[158:161], v155 offset:2048
	ds_read_b128 v[166:169], v155 offset:3072
	s_add_u32 s24, vcc_lo, 0xfffc0080
	s_addc_u32 s25, vcc_hi, -1
	s_cmp_eq_u32 s23, 12
	s_cselect_b32 s31, s20, s25
	s_cselect_b32 s30, s21, s24
	s_cselect_b32 s29, s27, s22
	s_cselect_b32 s28, s42, s87
	s_add_i32 m0, s72, 0xc000
	ds_read_b128 v[170:173], v154
	ds_read_b128 v[174:177], v154 offset:1024
	ds_read_b128 v[178:181], v154 offset:2048
	ds_read_b128 v[182:185], v154 offset:3072
	ds_read_b128 v[186:189], v154 offset:4096
	ds_read_b128 v[190:193], v154 offset:5120
	ds_read_b128 v[194:197], v154 offset:6144
	ds_read_b128 v[198:201], v154 offset:7168
	global_load_lds_dwordx4 v142, vcc
	s_add_i32 m0, s72, 0xe000
	s_nop 0
	global_load_lds_dwordx4 v144, vcc
	s_barrier
	s_waitcnt lgkmcnt(0)
	s_waitcnt lgkmcnt(0)
	v_mfma_f32_16x16x32_bf16 v[130:133], v[50:53], v[170:173], v[130:133]
	v_mfma_f32_16x16x32_bf16 v[122:125], v[158:161], v[170:173], v[122:125]
	v_mfma_f32_16x16x32_bf16 v[114:117], v[50:53], v[178:181], v[114:117]
	v_mfma_f32_16x16x32_bf16 v[106:109], v[158:161], v[178:181], v[106:109]
	v_mfma_f32_16x16x32_bf16 v[98:101], v[50:53], v[186:189], v[98:101]
	v_mfma_f32_16x16x32_bf16 v[90:93], v[158:161], v[186:189], v[90:93]
	v_mfma_f32_16x16x32_bf16 v[82:85], v[50:53], v[194:197], v[82:85]
	v_mfma_f32_16x16x32_bf16 v[74:77], v[158:161], v[194:197], v[74:77]
	v_mfma_f32_16x16x32_bf16 v[130:133], v[146:149], v[174:177], v[130:133]
	v_mfma_f32_16x16x32_bf16 v[122:125], v[166:169], v[174:177], v[122:125]
	v_mfma_f32_16x16x32_bf16 v[114:117], v[146:149], v[182:185], v[114:117]
	v_mfma_f32_16x16x32_bf16 v[106:109], v[166:169], v[182:185], v[106:109]
	v_mfma_f32_16x16x32_bf16 v[98:101], v[146:149], v[190:193], v[98:101]
	v_mfma_f32_16x16x32_bf16 v[90:93], v[166:169], v[190:193], v[90:93]
	v_mfma_f32_16x16x32_bf16 v[82:85], v[146:149], v[198:201], v[82:85]
	v_mfma_f32_16x16x32_bf16 v[74:77], v[166:169], v[198:201], v[74:77]
	s_barrier
	s_mov_b32 m0, s14
	ds_read_b128 v[202:205], v155 offset:16384
	ds_read_b128 v[206:209], v155 offset:17408
	ds_read_b128 v[210:213], v155 offset:18432
	ds_read_b128 v[214:217], v155 offset:19456
	global_load_lds_dwordx4 v0, s[28:29]
	s_mov_b32 m0, s15
	s_nop 0
	global_load_lds_dwordx4 v138, s[28:29]
	s_barrier
	s_waitcnt lgkmcnt(0)
	v_mfma_f32_16x16x32_bf16 v[126:129], v[202:205], v[170:173], v[126:129]
	v_mfma_f32_16x16x32_bf16 v[118:121], v[210:213], v[170:173], v[118:121]
	v_mfma_f32_16x16x32_bf16 v[110:113], v[202:205], v[178:181], v[110:113]
	v_mfma_f32_16x16x32_bf16 v[102:105], v[210:213], v[178:181], v[102:105]
	v_mfma_f32_16x16x32_bf16 v[94:97], v[202:205], v[186:189], v[94:97]
	v_mfma_f32_16x16x32_bf16 v[86:89], v[210:213], v[186:189], v[86:89]
	v_mfma_f32_16x16x32_bf16 v[78:81], v[202:205], v[194:197], v[78:81]
	v_mfma_f32_16x16x32_bf16 v[70:73], v[210:213], v[194:197], v[70:73]
	v_mfma_f32_16x16x32_bf16 v[126:129], v[206:209], v[174:177], v[126:129]
	v_mfma_f32_16x16x32_bf16 v[118:121], v[214:217], v[174:177], v[118:121]
	v_mfma_f32_16x16x32_bf16 v[110:113], v[206:209], v[182:185], v[110:113]
	v_mfma_f32_16x16x32_bf16 v[102:105], v[214:217], v[182:185], v[102:105]
	v_mfma_f32_16x16x32_bf16 v[94:97], v[206:209], v[190:193], v[94:97]
	v_mfma_f32_16x16x32_bf16 v[86:89], v[214:217], v[190:193], v[86:89]
	v_mfma_f32_16x16x32_bf16 v[78:81], v[206:209], v[198:201], v[78:81]
	v_mfma_f32_16x16x32_bf16 v[70:73], v[214:217], v[198:201], v[70:73]
	s_mov_b32 m0, s72
	s_barrier
	ds_read_b128 v[170:173], v154 offset:16384
	ds_read_b128 v[174:177], v154 offset:17408
	ds_read_b128 v[178:181], v154 offset:18432
	ds_read_b128 v[182:185], v154 offset:19456
	ds_read_b128 v[186:189], v154 offset:20480
	ds_read_b128 v[190:193], v154 offset:21504
	ds_read_b128 v[194:197], v154 offset:22528
	ds_read_b128 v[198:201], v154 offset:23552
	global_load_lds_dwordx4 v134, s[30:31]
	s_mov_b32 m0, s58
	s_nop 0
	global_load_lds_dwordx4 v136, s[30:31]
	s_barrier
	s_waitcnt lgkmcnt(0)
	v_mfma_f32_16x16x32_bf16 v[66:69], v[50:53], v[170:173], v[66:69]
	v_mfma_f32_16x16x32_bf16 v[58:61], v[158:161], v[170:173], v[58:61]
	v_mfma_f32_16x16x32_bf16 v[46:49], v[50:53], v[178:181], v[46:49]
	v_mfma_f32_16x16x32_bf16 v[38:41], v[158:161], v[178:181], v[38:41]
	v_mfma_f32_16x16x32_bf16 v[30:33], v[50:53], v[186:189], v[30:33]
	v_mfma_f32_16x16x32_bf16 v[22:25], v[158:161], v[186:189], v[22:25]
	v_mfma_f32_16x16x32_bf16 v[14:17], v[50:53], v[194:197], v[14:17]
	v_mfma_f32_16x16x32_bf16 v[6:9], v[158:161], v[194:197], v[6:9]
	v_mfma_f32_16x16x32_bf16 v[66:69], v[146:149], v[174:177], v[66:69]
	v_mfma_f32_16x16x32_bf16 v[58:61], v[166:169], v[174:177], v[58:61]
	v_mfma_f32_16x16x32_bf16 v[46:49], v[146:149], v[182:185], v[46:49]
	v_mfma_f32_16x16x32_bf16 v[38:41], v[166:169], v[182:185], v[38:41]
	v_mfma_f32_16x16x32_bf16 v[30:33], v[146:149], v[190:193], v[30:33]
	v_mfma_f32_16x16x32_bf16 v[22:25], v[166:169], v[190:193], v[22:25]
	v_mfma_f32_16x16x32_bf16 v[14:17], v[146:149], v[198:201], v[14:17]
	v_mfma_f32_16x16x32_bf16 v[6:9], v[166:169], v[198:201], v[6:9]
	s_barrier
	s_add_u32 s24, s28, 0x40000
	s_addc_u32 s25, s29, 0
	s_mov_b32 m0, s59
	s_nop 0
	global_load_lds_dwordx4 v0, s[24:25]
	s_mov_b32 m0, s62
	s_nop 0
	global_load_lds_dwordx4 v138, s[24:25]
	s_waitcnt vmcnt(6)
	s_barrier
	v_mfma_f32_16x16x32_bf16 v[54:57], v[210:213], v[170:173], v[54:57]
	v_mfma_f32_16x16x32_bf16 v[42:45], v[202:205], v[178:181], v[42:45]
	v_mfma_f32_16x16x32_bf16 v[34:37], v[210:213], v[178:181], v[34:37]
	v_mfma_f32_16x16x32_bf16 v[26:29], v[202:205], v[186:189], v[26:29]
	v_mfma_f32_16x16x32_bf16 v[18:21], v[210:213], v[186:189], v[18:21]
	v_mfma_f32_16x16x32_bf16 v[10:13], v[202:205], v[194:197], v[10:13]
	v_mfma_f32_16x16x32_bf16 v[2:5], v[210:213], v[194:197], v[2:5]
	v_mfma_f32_16x16x32_bf16 v[50:53], v[202:205], v[170:173], v[62:65]
	v_mfma_f32_16x16x32_bf16 v[54:57], v[214:217], v[174:177], v[54:57]
	v_mfma_f32_16x16x32_bf16 v[42:45], v[206:209], v[182:185], v[42:45]
	v_mfma_f32_16x16x32_bf16 v[34:37], v[214:217], v[182:185], v[34:37]
	v_mfma_f32_16x16x32_bf16 v[26:29], v[206:209], v[190:193], v[26:29]
	v_mfma_f32_16x16x32_bf16 v[18:21], v[214:217], v[190:193], v[18:21]
	v_mfma_f32_16x16x32_bf16 v[10:13], v[206:209], v[198:201], v[10:13]
	v_mfma_f32_16x16x32_bf16 v[2:5], v[214:217], v[198:201], v[2:5]
	v_mfma_f32_16x16x32_bf16 v[50:53], v[206:209], v[174:177], v[50:53]
	s_barrier
; #define PG8_STAGE(bufoff, gbase, voff) do { _Pragma("unroll") for (int _i = 0; _i < 2; ++_i) \
;     __builtin_amdgcn_global_load_lds((const unsigned*)((const char*)(gbase) + (voff)[_i]), (PG8_LAS unsigned*)(lds + (bufoff) + ldsw + _i * 8192), 16, 0, 0); } while (0)
; #define PG8_LDA(dst, b, h) do { _Pragma("unroll") for (int m = 0; m < 4; ++m) _Pragma("unroll") for (int k = 0; k < 2; ++k) dst[m][k] = *(const PG8_LAS bf16x8*)(lds + PG8_SA(b, h) + aoff + m * 2048 + k * 1024); } while (0)
; #define PG8_LDB(dst, b, h) do { _Pragma("unroll") for (int n = 0; n < 2; ++n) _Pragma("unroll") for (int k = 0; k < 2; ++k) dst[n][k] = *(const PG8_LAS bf16x8*)(lds + PG8_SB(b, h) + boff + n * 2048 + k * 1024); } while (0)
; template <class Epi>
; DI void gemm_phase(const bf16_t* __restrict__ gA, const bf16_t* __restrict__ gBt, int M, int N, int K, const Epi& E, char* lds_generic) {
;     ...
;     for (int t = 0; t < nt; t += 2) {
;       const bool last = (t == nt - 2);
;       const char* a1 = cA + (size_t)(t + 1) * kstep;
;       const char* a2 = last ? nA : cA + (size_t)(t + 2) * kstep; const char* b2 = last ? nB : cB + (size_t)(t + 2) * kstep;
;       const char* a3 = a2 + kstep; const char* b3 = b2 + kstep;
;       PG8_LDB(B0, 0, 0); PG8_SCHED; PG8_LDA(At, 0, 0); PG8_STAGE(PG8_SA(1, 1), a1 + hstep, voffA);
;       PG8_WAIT_L(8); PG8_BAR; PG8_WAIT_L(0); PG8_MMA(0, 0, At, B0); PG8_BAR; PG8_SCHED;
;       PG8_LDB(B1, 0, 1); PG8_STAGE(PG8_SB(0, 0), b2, voffB);
;       PG8_BAR; PG8_WAIT_L(0); PG8_MMA(0, 1, At, B1); PG8_BAR;
;       PG8_LDA(At, 0, 1); PG8_STAGE(PG8_SA(0, 0), a2, voffA);
;       PG8_BAR; PG8_WAIT_L(0); PG8_MMA(1, 0, At, B0); PG8_BAR; PG8_SCHED;
;       PG8_STAGE(PG8_SB(0, 1), b2 + hstep, voffB);
;       PG8_WAIT_V(6); PG8_BAR; PG8_MMA(1, 1, At, B1); PG8_BAR;
;       PG8_LDB(B0, 1, 0); PG8_SCHED; PG8_LDA(At, 1, 0); PG8_STAGE(PG8_SA(0, 1), a2 + hstep, voffA);
;       PG8_WAIT_L(8); PG8_BAR; PG8_WAIT_L(0); PG8_MMA(0, 0, At, B0); PG8_BAR; PG8_SCHED;
;       PG8_LDB(B1, 1, 1); PG8_STAGE(PG8_SB(1, 0), b3, voffB);
;       PG8_BAR; PG8_WAIT_L(0); PG8_MMA(0, 1, At, B1); PG8_BAR;
;       PG8_LDA(At, 1, 1); PG8_STAGE(PG8_SA(1, 0), a3, voffA);
;       PG8_BAR; PG8_WAIT_L(0); PG8_MMA(1, 0, At, B0); PG8_BAR; PG8_SCHED;
;       PG8_STAGE(PG8_SB(1, 1), b3 + hstep, voffB);
;       PG8_WAIT_V(6); PG8_BAR; PG8_MMA(1, 1, At, B1); PG8_BAR;
.Lup605_p5:
	ds_read_b128 v[62:65], v155 offset:32768
	ds_read_b128 v[146:149], v155 offset:33792
	ds_read_b128 v[158:161], v155 offset:34816
	ds_read_b128 v[166:169], v155 offset:35840
	s_add_u32 s24, s30, 0x40000
	s_addc_u32 s25, s31, 0
	s_mov_b32 m0, s7
	ds_read_b128 v[170:173], v154 offset:32768
	ds_read_b128 v[174:177], v154 offset:33792
	ds_read_b128 v[178:181], v154 offset:34816
	ds_read_b128 v[182:185], v154 offset:35840
	ds_read_b128 v[186:189], v154 offset:36864
	ds_read_b128 v[190:193], v154 offset:37888
	ds_read_b128 v[194:197], v154 offset:38912
	ds_read_b128 v[198:201], v154 offset:39936
	global_load_lds_dwordx4 v134, s[24:25]
	s_mov_b32 m0, s12
	s_nop 0
	global_load_lds_dwordx4 v136, s[24:25]
	s_barrier
	s_waitcnt lgkmcnt(0)
	s_waitcnt lgkmcnt(0)
	v_mfma_f32_16x16x32_bf16 v[130:133], v[62:65], v[170:173], v[130:133]
	v_mfma_f32_16x16x32_bf16 v[122:125], v[158:161], v[170:173], v[122:125]
	v_mfma_f32_16x16x32_bf16 v[114:117], v[62:65], v[178:181], v[114:117]
	v_mfma_f32_16x16x32_bf16 v[106:109], v[158:161], v[178:181], v[106:109]
	v_mfma_f32_16x16x32_bf16 v[98:101], v[62:65], v[186:189], v[98:101]
	v_mfma_f32_16x16x32_bf16 v[90:93], v[158:161], v[186:189], v[90:93]
	v_mfma_f32_16x16x32_bf16 v[82:85], v[62:65], v[194:197], v[82:85]
	v_mfma_f32_16x16x32_bf16 v[74:77], v[158:161], v[194:197], v[74:77]
	v_mfma_f32_16x16x32_bf16 v[130:133], v[146:149], v[174:177], v[130:133]
	v_mfma_f32_16x16x32_bf16 v[122:125], v[166:169], v[174:177], v[122:125]
	v_mfma_f32_16x16x32_bf16 v[114:117], v[146:149], v[182:185], v[114:117]
	v_mfma_f32_16x16x32_bf16 v[106:109], v[166:169], v[182:185], v[106:109]
	v_mfma_f32_16x16x32_bf16 v[98:101], v[146:149], v[190:193], v[98:101]
	v_mfma_f32_16x16x32_bf16 v[90:93], v[166:169], v[190:193], v[90:93]
	v_mfma_f32_16x16x32_bf16 v[82:85], v[146:149], v[198:201], v[82:85]
	v_mfma_f32_16x16x32_bf16 v[74:77], v[166:169], v[198:201], v[74:77]
	s_barrier
	s_mov_b32 m0, s13
	ds_read_b128 v[202:205], v155 offset:49152
	ds_read_b128 v[206:209], v155 offset:50176
	ds_read_b128 v[210:213], v155 offset:51200
	ds_read_b128 v[214:217], v155 offset:52224
	s_add_u32 s24, s28, 0x80
	s_addc_u32 s25, s29, 0
	global_load_lds_dwordx4 v0, s[24:25]
	s_mov_b32 m0, s35
	s_nop 0
	s_add_u32 s24, s28, 0x80
	s_addc_u32 s25, s29, 0
	global_load_lds_dwordx4 v138, s[24:25]
	s_barrier
	s_waitcnt lgkmcnt(0)
	v_mfma_f32_16x16x32_bf16 v[126:129], v[202:205], v[170:173], v[126:129]
	v_mfma_f32_16x16x32_bf16 v[118:121], v[210:213], v[170:173], v[118:121]
	v_mfma_f32_16x16x32_bf16 v[110:113], v[202:205], v[178:181], v[110:113]
	v_mfma_f32_16x16x32_bf16 v[102:105], v[210:213], v[178:181], v[102:105]
	v_mfma_f32_16x16x32_bf16 v[94:97], v[202:205], v[186:189], v[94:97]
	v_mfma_f32_16x16x32_bf16 v[86:89], v[210:213], v[186:189], v[86:89]
	v_mfma_f32_16x16x32_bf16 v[78:81], v[202:205], v[194:197], v[78:81]
	v_mfma_f32_16x16x32_bf16 v[70:73], v[210:213], v[194:197], v[70:73]
	v_mfma_f32_16x16x32_bf16 v[126:129], v[206:209], v[174:177], v[126:129]
	v_mfma_f32_16x16x32_bf16 v[118:121], v[214:217], v[174:177], v[118:121]
	v_mfma_f32_16x16x32_bf16 v[110:113], v[206:209], v[182:185], v[110:113]
	v_mfma_f32_16x16x32_bf16 v[102:105], v[214:217], v[182:185], v[102:105]
	v_mfma_f32_16x16x32_bf16 v[94:97], v[206:209], v[190:193], v[94:97]
	v_mfma_f32_16x16x32_bf16 v[86:89], v[214:217], v[190:193], v[86:89]
	v_mfma_f32_16x16x32_bf16 v[78:81], v[206:209], v[198:201], v[78:81]
	v_mfma_f32_16x16x32_bf16 v[70:73], v[214:217], v[198:201], v[70:73]
	s_mov_b32 m0, s53
	s_barrier
; #define PG8_STAGE(bufoff, gbase, voff) do { _Pragma("unroll") for (int _i = 0; _i < 2; ++_i) \
;     __builtin_amdgcn_global_load_lds((const unsigned*)((const char*)(gbase) + (voff)[_i]), (PG8_LAS unsigned*)(lds + (bufoff) + ldsw + _i * 8192), 16, 0, 0); } while (0)
; #define PG8_LDA(dst, b, h) do { _Pragma("unroll") for (int m = 0; m < 4; ++m) _Pragma("unroll") for (int k = 0; k < 2; ++k) dst[m][k] = *(const PG8_LAS bf16x8*)(lds + PG8_SA(b, h) + aoff + m * 2048 + k * 1024); } while (0)
; #define PG8_WAIT_V(n) asm volatile("s_waitcnt vmcnt(" #n ")" ::: "memory")
; #define PG8_WAIT_L(n) asm volatile("s_waitcnt lgkmcnt(" #n ")" ::: "memory")
; template <class Epi>
; DI void gemm_phase(const bf16_t* __restrict__ gA, const bf16_t* __restrict__ gBt, int M, int N, int K, const Epi& E, char* lds_generic) {
;     ...
;     for (int t = 0; t < nt; t += 2) {
;       const bool last = (t == nt - 2);
;       const char* a1 = cA + (size_t)(t + 1) * kstep;
;       const char* a2 = last ? nA : cA + (size_t)(t + 2) * kstep; const char* b2 = last ? nB : cB + (size_t)(t + 2) * kstep;
;       const char* a3 = a2 + kstep; const char* b3 = b2 + kstep;
;       PG8_LDB(B0, 0, 0); PG8_SCHED; PG8_LDA(At, 0, 0); PG8_STAGE(PG8_SA(1, 1), a1 + hstep, voffA);
;       PG8_WAIT_L(8); PG8_BAR; PG8_WAIT_L(0); PG8_MMA(0, 0, At, B0); PG8_BAR; PG8_SCHED;
;       PG8_LDB(B1, 0, 1); PG8_STAGE(PG8_SB(0, 0), b2, voffB);
;       PG8_BAR; PG8_WAIT_L(0); PG8_MMA(0, 1, At, B1); PG8_BAR;
;       PG8_LDA(At, 0, 1); PG8_STAGE(PG8_SA(0, 0), a2, voffA);
;       PG8_BAR; PG8_WAIT_L(0); PG8_MMA(1, 0, At, B0); PG8_BAR; PG8_SCHED;
;       PG8_STAGE(PG8_SB(0, 1), b2 + hstep, voffB);
;       PG8_WAIT_V(6); PG8_BAR; PG8_MMA(1, 1, At, B1); PG8_BAR;
;       PG8_LDB(B0, 1, 0); PG8_SCHED; PG8_LDA(At, 1, 0); PG8_STAGE(PG8_SA(0, 1), a2 + hstep, voffA);
;       PG8_WAIT_L(8); PG8_BAR; PG8_WAIT_L(0); PG8_MMA(0, 0, At, B0); PG8_BAR; PG8_SCHED;
;       PG8_LDB(B1, 1, 1); PG8_STAGE(PG8_SB(1, 0), b3, voffB);
;       PG8_BAR; PG8_WAIT_L(0); PG8_MMA(0, 1, At, B1); PG8_BAR;
;       PG8_LDA(At, 1, 1); PG8_STAGE(PG8_SA(1, 0), a3, voffA);
;       PG8_BAR; PG8_WAIT_L(0); PG8_MMA(1, 0, At, B0); PG8_BAR; PG8_SCHED;
;       PG8_STAGE(PG8_SB(1, 1), b3 + hstep, voffB);
;       PG8_WAIT_V(6); PG8_BAR; PG8_MMA(1, 1, At, B1); PG8_BAR;
;     }
;     uint4 rtn_ = {0u, 0u, 0u, 0u};
;     if (has_next) PG8_RTAB_LOAD(rtn_, nxt);
	ds_read_b128 v[170:173], v154 offset:49152
	ds_read_b128 v[174:177], v154 offset:50176
	ds_read_b128 v[178:181], v154 offset:51200
	ds_read_b128 v[182:185], v154 offset:52224
	ds_read_b128 v[186:189], v154 offset:53248
	ds_read_b128 v[190:193], v154 offset:54272
	ds_read_b128 v[194:197], v154 offset:55296
	ds_read_b128 v[198:201], v154 offset:56320
	s_add_u32 s24, s30, 0x80
	s_addc_u32 s25, s31, 0
	global_load_lds_dwordx4 v134, s[24:25]
	s_mov_b32 m0, s74
	s_nop 0
	s_add_u32 s24, s30, 0x80
	s_addc_u32 s25, s31, 0
	global_load_lds_dwordx4 v136, s[24:25]
	s_barrier
	s_waitcnt lgkmcnt(0)
	v_mfma_f32_16x16x32_bf16 v[66:69], v[62:65], v[170:173], v[66:69]
	v_mfma_f32_16x16x32_bf16 v[58:61], v[158:161], v[170:173], v[58:61]
	v_mfma_f32_16x16x32_bf16 v[46:49], v[62:65], v[178:181], v[46:49]
	v_mfma_f32_16x16x32_bf16 v[38:41], v[158:161], v[178:181], v[38:41]
	v_mfma_f32_16x16x32_bf16 v[30:33], v[62:65], v[186:189], v[30:33]
	v_mfma_f32_16x16x32_bf16 v[22:25], v[158:161], v[186:189], v[22:25]
	v_mfma_f32_16x16x32_bf16 v[14:17], v[62:65], v[194:197], v[14:17]
	v_mfma_f32_16x16x32_bf16 v[6:9], v[158:161], v[194:197], v[6:9]
	v_mfma_f32_16x16x32_bf16 v[66:69], v[146:149], v[174:177], v[66:69]
	v_mfma_f32_16x16x32_bf16 v[58:61], v[166:169], v[174:177], v[58:61]
	v_mfma_f32_16x16x32_bf16 v[46:49], v[146:149], v[182:185], v[46:49]
	v_mfma_f32_16x16x32_bf16 v[38:41], v[166:169], v[182:185], v[38:41]
	v_mfma_f32_16x16x32_bf16 v[30:33], v[146:149], v[190:193], v[30:33]
	v_mfma_f32_16x16x32_bf16 v[22:25], v[166:169], v[190:193], v[22:25]
	v_mfma_f32_16x16x32_bf16 v[14:17], v[146:149], v[198:201], v[14:17]
	v_mfma_f32_16x16x32_bf16 v[6:9], v[166:169], v[198:201], v[6:9]
	s_barrier
	s_add_u32 s24, s28, 0x40080
	s_addc_u32 s25, s29, 0
	s_mov_b32 m0, s60
	s_nop 0
	global_load_lds_dwordx4 v0, s[24:25]
	s_mov_b32 m0, s6
	s_nop 0
	global_load_lds_dwordx4 v138, s[24:25]
	s_waitcnt vmcnt(6)
	s_barrier
	v_mfma_f32_16x16x32_bf16 v[50:53], v[202:205], v[170:173], v[50:53]
	v_mfma_f32_16x16x32_bf16 v[62:65], v[206:209], v[174:177], v[50:53]
	v_mfma_f32_16x16x32_bf16 v[50:53], v[210:213], v[170:173], v[54:57]
	v_mfma_f32_16x16x32_bf16 v[42:45], v[202:205], v[178:181], v[42:45]
	v_mfma_f32_16x16x32_bf16 v[34:37], v[210:213], v[178:181], v[34:37]
	v_mfma_f32_16x16x32_bf16 v[26:29], v[202:205], v[186:189], v[26:29]
	v_mfma_f32_16x16x32_bf16 v[18:21], v[210:213], v[186:189], v[18:21]
	v_mfma_f32_16x16x32_bf16 v[10:13], v[202:205], v[194:197], v[10:13]
	v_mfma_f32_16x16x32_bf16 v[2:5], v[210:213], v[194:197], v[2:5]
	v_mfma_f32_16x16x32_bf16 v[54:57], v[214:217], v[174:177], v[50:53]
	v_mfma_f32_16x16x32_bf16 v[42:45], v[206:209], v[182:185], v[42:45]
	v_mfma_f32_16x16x32_bf16 v[34:37], v[214:217], v[182:185], v[34:37]
	v_mfma_f32_16x16x32_bf16 v[26:29], v[206:209], v[190:193], v[26:29]
	v_mfma_f32_16x16x32_bf16 v[18:21], v[214:217], v[190:193], v[18:21]
	v_mfma_f32_16x16x32_bf16 v[10:13], v[206:209], v[198:201], v[10:13]
	v_mfma_f32_16x16x32_bf16 v[2:5], v[214:217], v[198:201], v[2:5]
	s_add_i32 s23, s23, 2
	s_add_u32 vcc_lo, vcc_lo, 0x100
	s_addc_u32 vcc_hi, vcc_hi, 0
	s_add_u32 s87, s87, 0x100
	s_addc_u32 s22, s22, 0
	s_cmp_gt_u32 s23, 13
	s_barrier
	s_cbranch_scc0 .LBB0_605
	v_mov_b32_e32 v50, 0
	s_and_b64 vcc, exec, s[38:39]
	v_mov_b32_e32 v51, 0
	v_mov_b32_e32 v52, 0
	v_mov_b32_e32 v53, 0
	s_cbranch_vccz .LBB0_608
	v_lshl_add_u32 v50, s86, 8, v150
	v_ashrrev_i32_e32 v51, 31, v50
	v_lshlrev_b64 v[50:51], 5, v[50:51]
	v_lshl_add_u64 v[50:51], v[140:141], 0, v[50:51]
	global_load_dwordx4 v[50:53], v[50:51], off

; #define PG8_STAGE(bufoff, gbase, voff) do { _Pragma("unroll") for (int _i = 0; _i < 2; ++_i) \
;     __builtin_amdgcn_global_load_lds((const unsigned*)((const char*)(gbase) + (voff)[_i]), (PG8_LAS unsigned*)(lds + (bufoff) + ldsw + _i * 8192), 16, 0, 0); } while (0)
; #define PG8_LDA(dst, b, h) do { _Pragma("unroll") for (int m = 0; m < 4; ++m) _Pragma("unroll") for (int k = 0; k < 2; ++k) dst[m][k] = *(const PG8_LAS bf16x8*)(lds + PG8_SA(b, h) + aoff + m * 2048 + k * 1024); } while (0)
; #define PG8_LDB(dst, b, h) do { _Pragma("unroll") for (int n = 0; n < 2; ++n) _Pragma("unroll") for (int k = 0; k < 2; ++k) dst[n][k] = *(const PG8_LAS bf16x8*)(lds + PG8_SB(b, h) + boff + n * 2048 + k * 1024); } while (0)
; template <class Epi>
; DI void gemm_phase(const bf16_t* __restrict__ gA, const bf16_t* __restrict__ gBt, int M, int N, int K, const Epi& E, char* lds_generic) {
;     ...
;     for (int t = 0; t < nt; t += 2) {
;       const bool last = (t == nt - 2);
;       const char* a1 = cA + (size_t)(t + 1) * kstep;
;       const char* a2 = last ? nA : cA + (size_t)(t + 2) * kstep; const char* b2 = last ? nB : cB + (size_t)(t + 2) * kstep;
;       const char* a3 = a2 + kstep; const char* b3 = b2 + kstep;
;       PG8_LDB(B0, 0, 0); PG8_SCHED; PG8_LDA(At, 0, 0); PG8_STAGE(PG8_SA(1, 1), a1 + hstep, voffA);
;       PG8_WAIT_L(8); PG8_BAR; PG8_WAIT_L(0); PG8_MMA(0, 0, At, B0); PG8_BAR; PG8_SCHED;
;       PG8_LDB(B1, 0, 1); PG8_STAGE(PG8_SB(0, 0), b2, voffB);
;       PG8_BAR; PG8_WAIT_L(0); PG8_MMA(0, 1, At, B1); PG8_BAR;
;       PG8_LDA(At, 0, 1); PG8_STAGE(PG8_SA(0, 0), a2, voffA);
;       PG8_BAR; PG8_WAIT_L(0); PG8_MMA(1, 0, At, B0); PG8_BAR; PG8_SCHED;
;       PG8_STAGE(PG8_SB(0, 1), b2 + hstep, voffB);
;       PG8_WAIT_V(6); PG8_BAR; PG8_MMA(1, 1, At, B1); PG8_BAR;
;       PG8_LDB(B0, 1, 0); PG8_SCHED; PG8_LDA(At, 1, 0); PG8_STAGE(PG8_SA(0, 1), a2 + hstep, voffA);
;       PG8_WAIT_L(8); PG8_BAR; PG8_WAIT_L(0); PG8_MMA(0, 0, At, B0); PG8_BAR; PG8_SCHED;
;       PG8_LDB(B1, 1, 1); PG8_STAGE(PG8_SB(1, 0), b3, voffB);
;       PG8_BAR; PG8_WAIT_L(0); PG8_MMA(0, 1, At, B1); PG8_BAR;
;       PG8_LDA(At, 1, 1); PG8_STAGE(PG8_SA(1, 0), a3, voffA);
;       PG8_BAR; PG8_WAIT_L(0); PG8_MMA(1, 0, At, B0); PG8_BAR; PG8_SCHED;
;       PG8_STAGE(PG8_SB(1, 1), b3 + hstep, voffB);
;       PG8_WAIT_V(6); PG8_BAR; PG8_MMA(1, 1, At, B1); PG8_BAR;
.LBB0_684:
	ds_read_b128 v[140:143], v146
	ds_read_b128 v[148:151], v146 offset:1024
	ds_read_b128 v[152:155], v146 offset:2048
	ds_read_b128 v[156:159], v146 offset:3072
	s_add_u32 s28, s88, 0x100
	s_addc_u32 s29, s89, 0
	s_cmp_eq_u32 s23, 40
	s_cselect_b32 s91, s87, s29
	s_cselect_b32 s90, s86, s28
	s_cselect_b32 s31, s1, s22
	s_cselect_b32 s30, s0, s21
	s_add_i32 m0, s12, 0xc000
	ds_read_b128 v[166:169], v145
	ds_read_b128 v[170:173], v145 offset:1024
	ds_read_b128 v[174:177], v145 offset:2048
	ds_read_b128 v[178:181], v145 offset:3072
	ds_read_b128 v[182:185], v145 offset:4096
	ds_read_b128 v[186:189], v145 offset:5120
	ds_read_b128 v[190:193], v145 offset:6144
	ds_read_b128 v[194:197], v145 offset:7168
	global_load_lds_dwordx4 v136, s[88:89]
	s_add_i32 m0, s12, 0xe000
	s_nop 0
	global_load_lds_dwordx4 v138, s[88:89]
	s_barrier
	s_waitcnt lgkmcnt(0)
	s_waitcnt lgkmcnt(0)
	v_mfma_f32_16x16x32_bf16 v[126:129], v[140:143], v[166:169], v[126:129]
	v_mfma_f32_16x16x32_bf16 v[122:125], v[152:155], v[166:169], v[122:125]
	v_mfma_f32_16x16x32_bf16 v[110:113], v[140:143], v[174:177], v[110:113]
	v_mfma_f32_16x16x32_bf16 v[106:109], v[152:155], v[174:177], v[106:109]
	v_mfma_f32_16x16x32_bf16 v[94:97], v[140:143], v[182:185], v[94:97]
	v_mfma_f32_16x16x32_bf16 v[90:93], v[152:155], v[182:185], v[90:93]
	v_mfma_f32_16x16x32_bf16 v[78:81], v[140:143], v[190:193], v[78:81]
	v_mfma_f32_16x16x32_bf16 v[74:77], v[152:155], v[190:193], v[74:77]
	v_mfma_f32_16x16x32_bf16 v[126:129], v[148:151], v[170:173], v[126:129]
	v_mfma_f32_16x16x32_bf16 v[122:125], v[156:159], v[170:173], v[122:125]
	v_mfma_f32_16x16x32_bf16 v[110:113], v[148:151], v[178:181], v[110:113]
	v_mfma_f32_16x16x32_bf16 v[106:109], v[156:159], v[178:181], v[106:109]
	v_mfma_f32_16x16x32_bf16 v[94:97], v[148:151], v[186:189], v[94:97]
	v_mfma_f32_16x16x32_bf16 v[90:93], v[156:159], v[186:189], v[90:93]
	v_mfma_f32_16x16x32_bf16 v[78:81], v[148:151], v[194:197], v[78:81]
	v_mfma_f32_16x16x32_bf16 v[74:77], v[156:159], v[194:197], v[74:77]
	s_barrier
	ds_read_b128 v[198:201], v146 offset:16384
	ds_read_b128 v[202:205], v146 offset:17408
	s_mov_b32 m0, s13
	ds_read_b128 v[206:209], v146 offset:18432
	ds_read_b128 v[210:213], v146 offset:19456
	global_load_lds_dwordx4 v0, s[30:31]
	s_mov_b32 m0, s14
	s_nop 0
	global_load_lds_dwordx4 v134, s[30:31]
	s_barrier
	s_waitcnt lgkmcnt(0)
	v_mfma_f32_16x16x32_bf16 v[118:121], v[198:201], v[166:169], v[118:121]
	v_mfma_f32_16x16x32_bf16 v[114:117], v[206:209], v[166:169], v[114:117]
	v_mfma_f32_16x16x32_bf16 v[102:105], v[198:201], v[174:177], v[102:105]
	v_mfma_f32_16x16x32_bf16 v[98:101], v[206:209], v[174:177], v[98:101]
	v_mfma_f32_16x16x32_bf16 v[86:89], v[198:201], v[182:185], v[86:89]
	v_mfma_f32_16x16x32_bf16 v[82:85], v[206:209], v[182:185], v[82:85]
	v_mfma_f32_16x16x32_bf16 v[70:73], v[198:201], v[190:193], v[70:73]
	v_mfma_f32_16x16x32_bf16 v[66:69], v[206:209], v[190:193], v[66:69]
	v_mfma_f32_16x16x32_bf16 v[118:121], v[202:205], v[170:173], v[118:121]
	v_mfma_f32_16x16x32_bf16 v[114:117], v[210:213], v[170:173], v[114:117]
	v_mfma_f32_16x16x32_bf16 v[102:105], v[202:205], v[178:181], v[102:105]
	v_mfma_f32_16x16x32_bf16 v[98:101], v[210:213], v[178:181], v[98:101]
	v_mfma_f32_16x16x32_bf16 v[86:89], v[202:205], v[186:189], v[86:89]
	v_mfma_f32_16x16x32_bf16 v[82:85], v[210:213], v[186:189], v[82:85]
	v_mfma_f32_16x16x32_bf16 v[70:73], v[202:205], v[194:197], v[70:73]
	v_mfma_f32_16x16x32_bf16 v[66:69], v[210:213], v[194:197], v[66:69]
	s_mov_b32 m0, s12
	s_barrier
	ds_read_b128 v[166:169], v145 offset:16384
	ds_read_b128 v[170:173], v145 offset:17408
	ds_read_b128 v[174:177], v145 offset:18432
	ds_read_b128 v[178:181], v145 offset:19456
	ds_read_b128 v[182:185], v145 offset:20480
	ds_read_b128 v[186:189], v145 offset:21504
	ds_read_b128 v[190:193], v145 offset:22528
	ds_read_b128 v[194:197], v145 offset:23552
	global_load_lds_dwordx4 v130, s[90:91]
	s_mov_b32 m0, s15
	s_nop 0
	global_load_lds_dwordx4 v132, s[90:91]
	s_barrier
	s_waitcnt lgkmcnt(0)
	v_mfma_f32_16x16x32_bf16 v[62:65], v[140:143], v[166:169], v[62:65]
	v_mfma_f32_16x16x32_bf16 v[58:61], v[152:155], v[166:169], v[58:61]
	v_mfma_f32_16x16x32_bf16 v[46:49], v[140:143], v[174:177], v[46:49]
	v_mfma_f32_16x16x32_bf16 v[42:45], v[152:155], v[174:177], v[42:45]
	v_mfma_f32_16x16x32_bf16 v[30:33], v[140:143], v[182:185], v[30:33]
	v_mfma_f32_16x16x32_bf16 v[26:29], v[152:155], v[182:185], v[26:29]
	v_mfma_f32_16x16x32_bf16 v[14:17], v[140:143], v[190:193], v[14:17]
	v_mfma_f32_16x16x32_bf16 v[10:13], v[152:155], v[190:193], v[10:13]
	v_mfma_f32_16x16x32_bf16 v[62:65], v[148:151], v[170:173], v[62:65]
	v_mfma_f32_16x16x32_bf16 v[58:61], v[156:159], v[170:173], v[58:61]
	v_mfma_f32_16x16x32_bf16 v[46:49], v[148:151], v[178:181], v[46:49]
	v_mfma_f32_16x16x32_bf16 v[42:45], v[156:159], v[178:181], v[42:45]
	v_mfma_f32_16x16x32_bf16 v[30:33], v[148:151], v[186:189], v[30:33]
	v_mfma_f32_16x16x32_bf16 v[26:29], v[156:159], v[186:189], v[26:29]
	v_mfma_f32_16x16x32_bf16 v[14:17], v[148:151], v[194:197], v[14:17]
	v_mfma_f32_16x16x32_bf16 v[10:13], v[156:159], v[194:197], v[10:13]
	s_barrier
	s_add_u32 s24, s30, 0xb0000
	s_addc_u32 s25, s31, 0
	s_mov_b32 m0, s18
	s_nop 0
	global_load_lds_dwordx4 v0, s[24:25]
	s_mov_b32 m0, s35
	s_nop 0
	global_load_lds_dwordx4 v134, s[24:25]
	s_waitcnt vmcnt(6)
	s_barrier
; #define PG8_STAGE(bufoff, gbase, voff) do { _Pragma("unroll") for (int _i = 0; _i < 2; ++_i) \
;     __builtin_amdgcn_global_load_lds((const unsigned*)((const char*)(gbase) + (voff)[_i]), (PG8_LAS unsigned*)(lds + (bufoff) + ldsw + _i * 8192), 16, 0, 0); } while (0)
; #define PG8_LDA(dst, b, h) do { _Pragma("unroll") for (int m = 0; m < 4; ++m) _Pragma("unroll") for (int k = 0; k < 2; ++k) dst[m][k] = *(const PG8_LAS bf16x8*)(lds + PG8_SA(b, h) + aoff + m * 2048 + k * 1024); } while (0)
; #define PG8_LDB(dst, b, h) do { _Pragma("unroll") for (int n = 0; n < 2; ++n) _Pragma("unroll") for (int k = 0; k < 2; ++k) dst[n][k] = *(const PG8_LAS bf16x8*)(lds + PG8_SB(b, h) + boff + n * 2048 + k * 1024); } while (0)
; template <class Epi>
; DI void gemm_phase(const bf16_t* __restrict__ gA, const bf16_t* __restrict__ gBt, int M, int N, int K, const Epi& E, char* lds_generic) {
;     ...
;     for (int t = 0; t < nt; t += 2) {
;       const bool last = (t == nt - 2);
;       const char* a1 = cA + (size_t)(t + 1) * kstep;
;       const char* a2 = last ? nA : cA + (size_t)(t + 2) * kstep; const char* b2 = last ? nB : cB + (size_t)(t + 2) * kstep;
;       const char* a3 = a2 + kstep; const char* b3 = b2 + kstep;
;       PG8_LDB(B0, 0, 0); PG8_SCHED; PG8_LDA(At, 0, 0); PG8_STAGE(PG8_SA(1, 1), a1 + hstep, voffA);
;       PG8_WAIT_L(8); PG8_BAR; PG8_WAIT_L(0); PG8_MMA(0, 0, At, B0); PG8_BAR; PG8_SCHED;
;       PG8_LDB(B1, 0, 1); PG8_STAGE(PG8_SB(0, 0), b2, voffB);
;       PG8_BAR; PG8_WAIT_L(0); PG8_MMA(0, 1, At, B1); PG8_BAR;
;       PG8_LDA(At, 0, 1); PG8_STAGE(PG8_SA(0, 0), a2, voffA);
;       PG8_BAR; PG8_WAIT_L(0); PG8_MMA(1, 0, At, B0); PG8_BAR; PG8_SCHED;
;       PG8_STAGE(PG8_SB(0, 1), b2 + hstep, voffB);
;       PG8_WAIT_V(6); PG8_BAR; PG8_MMA(1, 1, At, B1); PG8_BAR;
;       PG8_LDB(B0, 1, 0); PG8_SCHED; PG8_LDA(At, 1, 0); PG8_STAGE(PG8_SA(0, 1), a2 + hstep, voffA);
;       PG8_WAIT_L(8); PG8_BAR; PG8_WAIT_L(0); PG8_MMA(0, 0, At, B0); PG8_BAR; PG8_SCHED;
;       PG8_LDB(B1, 1, 1); PG8_STAGE(PG8_SB(1, 0), b3, voffB);
;       PG8_BAR; PG8_WAIT_L(0); PG8_MMA(0, 1, At, B1); PG8_BAR;
;       PG8_LDA(At, 1, 1); PG8_STAGE(PG8_SA(1, 0), a3, voffA);
;       PG8_BAR; PG8_WAIT_L(0); PG8_MMA(1, 0, At, B0); PG8_BAR; PG8_SCHED;
;       PG8_STAGE(PG8_SB(1, 1), b3 + hstep, voffB);
;       PG8_WAIT_V(6); PG8_BAR; PG8_MMA(1, 1, At, B1); PG8_BAR;
	v_mfma_f32_16x16x32_bf16 v[54:57], v[198:201], v[166:169], v[54:57]
	v_mfma_f32_16x16x32_bf16 v[50:53], v[206:209], v[166:169], v[50:53]
	v_mfma_f32_16x16x32_bf16 v[38:41], v[198:201], v[174:177], v[38:41]
	v_mfma_f32_16x16x32_bf16 v[34:37], v[206:209], v[174:177], v[34:37]
	v_mfma_f32_16x16x32_bf16 v[22:25], v[198:201], v[182:185], v[22:25]
	v_mfma_f32_16x16x32_bf16 v[18:21], v[206:209], v[182:185], v[18:21]
	v_mfma_f32_16x16x32_bf16 v[6:9], v[198:201], v[190:193], v[6:9]
	v_mfma_f32_16x16x32_bf16 v[2:5], v[206:209], v[190:193], v[2:5]
	v_mfma_f32_16x16x32_bf16 v[54:57], v[202:205], v[170:173], v[54:57]
	v_mfma_f32_16x16x32_bf16 v[50:53], v[210:213], v[170:173], v[50:53]
	v_mfma_f32_16x16x32_bf16 v[38:41], v[202:205], v[178:181], v[38:41]
	v_mfma_f32_16x16x32_bf16 v[34:37], v[210:213], v[178:181], v[34:37]
	v_mfma_f32_16x16x32_bf16 v[22:25], v[202:205], v[186:189], v[22:25]
	v_mfma_f32_16x16x32_bf16 v[18:21], v[210:213], v[186:189], v[18:21]
	v_mfma_f32_16x16x32_bf16 v[6:9], v[202:205], v[194:197], v[6:9]
	v_mfma_f32_16x16x32_bf16 v[2:5], v[210:213], v[194:197], v[2:5]
	s_barrier
	ds_read_b128 v[140:143], v146 offset:32768
	ds_read_b128 v[148:151], v146 offset:33792
	ds_read_b128 v[152:155], v146 offset:34816
	ds_read_b128 v[156:159], v146 offset:35840
	s_add_u32 s24, s90, 0xb0000
	s_addc_u32 s25, s91, 0
	s_mov_b32 m0, s53
	ds_read_b128 v[166:169], v145 offset:32768
	ds_read_b128 v[170:173], v145 offset:33792
	ds_read_b128 v[174:177], v145 offset:34816
	ds_read_b128 v[178:181], v145 offset:35840
	ds_read_b128 v[182:185], v145 offset:36864
	ds_read_b128 v[186:189], v145 offset:37888
	ds_read_b128 v[190:193], v145 offset:38912
	ds_read_b128 v[194:197], v145 offset:39936
	global_load_lds_dwordx4 v130, s[24:25]
	s_mov_b32 m0, s58
	s_nop 0
	global_load_lds_dwordx4 v132, s[24:25]
	s_barrier
	s_waitcnt lgkmcnt(0)
	s_waitcnt lgkmcnt(0)
	v_mfma_f32_16x16x32_bf16 v[126:129], v[140:143], v[166:169], v[126:129]
	v_mfma_f32_16x16x32_bf16 v[122:125], v[152:155], v[166:169], v[122:125]
	v_mfma_f32_16x16x32_bf16 v[110:113], v[140:143], v[174:177], v[110:113]
	v_mfma_f32_16x16x32_bf16 v[106:109], v[152:155], v[174:177], v[106:109]
	v_mfma_f32_16x16x32_bf16 v[94:97], v[140:143], v[182:185], v[94:97]
	v_mfma_f32_16x16x32_bf16 v[90:93], v[152:155], v[182:185], v[90:93]
	v_mfma_f32_16x16x32_bf16 v[78:81], v[140:143], v[190:193], v[78:81]
	v_mfma_f32_16x16x32_bf16 v[74:77], v[152:155], v[190:193], v[74:77]
	v_mfma_f32_16x16x32_bf16 v[126:129], v[148:151], v[170:173], v[126:129]
	v_mfma_f32_16x16x32_bf16 v[122:125], v[156:159], v[170:173], v[122:125]
	v_mfma_f32_16x16x32_bf16 v[110:113], v[148:151], v[178:181], v[110:113]
	v_mfma_f32_16x16x32_bf16 v[106:109], v[156:159], v[178:181], v[106:109]
	v_mfma_f32_16x16x32_bf16 v[94:97], v[148:151], v[186:189], v[94:97]
	v_mfma_f32_16x16x32_bf16 v[90:93], v[156:159], v[186:189], v[90:93]
	v_mfma_f32_16x16x32_bf16 v[78:81], v[148:151], v[194:197], v[78:81]
	v_mfma_f32_16x16x32_bf16 v[74:77], v[156:159], v[194:197], v[74:77]
	s_barrier
	s_mov_b32 m0, s59
	ds_read_b128 v[198:201], v146 offset:49152
	ds_read_b128 v[202:205], v146 offset:50176
	ds_read_b128 v[206:209], v146 offset:51200
	ds_read_b128 v[210:213], v146 offset:52224
	s_add_u32 s24, s30, 0x80
	s_addc_u32 s25, s31, 0
	global_load_lds_dwordx4 v0, s[24:25]
	s_mov_b32 m0, s60
	s_nop 0
	s_add_u32 s24, s30, 0x80
	s_addc_u32 s25, s31, 0
	global_load_lds_dwordx4 v134, s[24:25]
	s_barrier
	s_waitcnt lgkmcnt(0)
	v_mfma_f32_16x16x32_bf16 v[118:121], v[198:201], v[166:169], v[118:121]
	v_mfma_f32_16x16x32_bf16 v[114:117], v[206:209], v[166:169], v[114:117]
	v_mfma_f32_16x16x32_bf16 v[102:105], v[198:201], v[174:177], v[102:105]
	v_mfma_f32_16x16x32_bf16 v[98:101], v[206:209], v[174:177], v[98:101]
	v_mfma_f32_16x16x32_bf16 v[86:89], v[198:201], v[182:185], v[86:89]
	v_mfma_f32_16x16x32_bf16 v[82:85], v[206:209], v[182:185], v[82:85]
	v_mfma_f32_16x16x32_bf16 v[70:73], v[198:201], v[190:193], v[70:73]
	v_mfma_f32_16x16x32_bf16 v[66:69], v[206:209], v[190:193], v[66:69]
	v_mfma_f32_16x16x32_bf16 v[118:121], v[202:205], v[170:173], v[118:121]
	v_mfma_f32_16x16x32_bf16 v[114:117], v[210:213], v[170:173], v[114:117]
	v_mfma_f32_16x16x32_bf16 v[102:105], v[202:205], v[178:181], v[102:105]
	v_mfma_f32_16x16x32_bf16 v[98:101], v[210:213], v[178:181], v[98:101]
	v_mfma_f32_16x16x32_bf16 v[86:89], v[202:205], v[186:189], v[86:89]
	v_mfma_f32_16x16x32_bf16 v[82:85], v[210:213], v[186:189], v[82:85]
	v_mfma_f32_16x16x32_bf16 v[70:73], v[202:205], v[194:197], v[70:73]
	v_mfma_f32_16x16x32_bf16 v[66:69], v[210:213], v[194:197], v[66:69]
	s_mov_b32 m0, s62
	s_barrier
; DI float bflo(unsigned u) { return __uint_as_float(u << 16); }
; DI float bfhi(unsigned u) { return __uint_as_float(u & 0xffff0000u); }
;   DI void init(f32x4 (&acc)[2][2][4][2], const Unit&, int, int, int, int) const { acc_zero(acc); }
;   DI void init(f32x4 (&acc)[2][2][4][2], const Unit&, int, int, int, int) const { acc_zero(acc); }
; #define PG8_STAGE(bufoff, gbase, voff) do { _Pragma("unroll") for (int _i = 0; _i < 2; ++_i) \
;     __builtin_amdgcn_global_load_lds((const unsigned*)((const char*)(gbase) + (voff)[_i]), (PG8_LAS unsigned*)(lds + (bufoff) + ldsw + _i * 8192), 16, 0, 0); } while (0)
; #define PG8_LDA(dst, b, h) do { _Pragma("unroll") for (int m = 0; m < 4; ++m) _Pragma("unroll") for (int k = 0; k < 2; ++k) dst[m][k] = *(const PG8_LAS bf16x8*)(lds + PG8_SA(b, h) + aoff + m * 2048 + k * 1024); } while (0)
; #define PG8_MMA(ai, bj, At, Bt) do { __builtin_amdgcn_s_setprio(1); _Pragma("unroll") for (int m = 0; m < 4; ++m) _Pragma("unroll") for (int n = 0; n < 2; ++n) _Pragma("unroll") for (int k = 0; k < 2; ++k) \
;     acc[ai][bj][m][n] = __builtin_amdgcn_mfma_f32_16x16x32_bf16(Bt[n][k], At[m][k], acc[ai][bj][m][n], 0, 0, 0); __builtin_amdgcn_s_setprio(0); } while (0)
; #define PG8_WAIT_V(n) asm volatile("s_waitcnt vmcnt(" #n ")" ::: "memory")
;   DI void init(f32x4 (&acc)[2][2][4][2], const Unit& u, int wr, int wc, int fr, int fq) const {
;     const int row0 = u.pm * BM + wr * 64 + fr, col0 = u.pn * BM + wc * 32 + 8 * fq; const float ic = 1.f / coef;
; #pragma unroll
;     for (int ai = 0; ai < 2; ++ai)
; #pragma unroll
;       for (int m = 0; m < 4; ++m) { const bf16_t* rowp = src + (size_t)(row0 + ai * HALF + m * 16) * DM + col0;
; #pragma unroll
;         for (int bj = 0; bj < 2; ++bj) { const u32x4 w = *(const u32x4*)(rowp + bj * HALF);
;           acc[ai][bj][m][0] = (f32x4){bflo(w.x), bfhi(w.x), bflo(w.y), bfhi(w.y)} * ic; acc[ai][bj][m][1] = (f32x4){bflo(w.z), bfhi(w.z), bflo(w.w), bfhi(w.w)} * ic; } }
; template <class Epi>
; DI void gemm_phase(const bf16_t* __restrict__ gA, const bf16_t* __restrict__ gBt, int M, int N, int K, const Epi& E, char* lds_generic) {
;     ...
;       PG8_LDA(At, 1, 1); PG8_STAGE(PG8_SA(1, 0), a3, voffA);
;       PG8_BAR; PG8_WAIT_L(0); PG8_MMA(1, 0, At, B0); PG8_BAR; PG8_SCHED;
;       PG8_STAGE(PG8_SB(1, 1), b3 + hstep, voffB);
;       PG8_WAIT_V(6); PG8_BAR; PG8_MMA(1, 1, At, B1); PG8_BAR;
;     }
	ds_read_b128 v[166:169], v145 offset:49152
	ds_read_b128 v[170:173], v145 offset:50176
	ds_read_b128 v[174:177], v145 offset:51200
	ds_read_b128 v[178:181], v145 offset:52224
	ds_read_b128 v[182:185], v145 offset:53248
	ds_read_b128 v[186:189], v145 offset:54272
	ds_read_b128 v[190:193], v145 offset:55296
	ds_read_b128 v[194:197], v145 offset:56320
	s_add_u32 s24, s90, 0x80
	s_addc_u32 s25, s91, 0
	global_load_lds_dwordx4 v130, s[24:25]
	s_mov_b32 m0, s72
	s_nop 0
	s_add_u32 s24, s90, 0x80
	s_addc_u32 s25, s91, 0
	global_load_lds_dwordx4 v132, s[24:25]
	s_barrier
	s_waitcnt lgkmcnt(0)
	v_mfma_f32_16x16x32_bf16 v[62:65], v[140:143], v[166:169], v[62:65]
	v_mfma_f32_16x16x32_bf16 v[58:61], v[152:155], v[166:169], v[58:61]
	v_mfma_f32_16x16x32_bf16 v[46:49], v[140:143], v[174:177], v[46:49]
	v_mfma_f32_16x16x32_bf16 v[42:45], v[152:155], v[174:177], v[42:45]
	v_mfma_f32_16x16x32_bf16 v[30:33], v[140:143], v[182:185], v[30:33]
	v_mfma_f32_16x16x32_bf16 v[26:29], v[152:155], v[182:185], v[26:29]
	v_mfma_f32_16x16x32_bf16 v[14:17], v[140:143], v[190:193], v[14:17]
	v_mfma_f32_16x16x32_bf16 v[10:13], v[152:155], v[190:193], v[10:13]
	v_mfma_f32_16x16x32_bf16 v[62:65], v[148:151], v[170:173], v[62:65]
	v_mfma_f32_16x16x32_bf16 v[58:61], v[156:159], v[170:173], v[58:61]
	v_mfma_f32_16x16x32_bf16 v[46:49], v[148:151], v[178:181], v[46:49]
	v_mfma_f32_16x16x32_bf16 v[42:45], v[156:159], v[178:181], v[42:45]
	v_mfma_f32_16x16x32_bf16 v[30:33], v[148:151], v[186:189], v[30:33]
	v_mfma_f32_16x16x32_bf16 v[26:29], v[156:159], v[186:189], v[26:29]
	v_mfma_f32_16x16x32_bf16 v[14:17], v[148:151], v[194:197], v[14:17]
	v_mfma_f32_16x16x32_bf16 v[10:13], v[156:159], v[194:197], v[10:13]
	s_barrier
	s_add_u32 s24, s30, 0xb0080
	s_addc_u32 s25, s31, 0
	s_mov_b32 m0, s74
	s_nop 0
	global_load_lds_dwordx4 v0, s[24:25]
	s_mov_b32 m0, s19
	s_nop 0
	global_load_lds_dwordx4 v134, s[24:25]
	s_waitcnt vmcnt(6)
	s_barrier
	v_mfma_f32_16x16x32_bf16 v[54:57], v[198:201], v[166:169], v[54:57]
	v_mfma_f32_16x16x32_bf16 v[50:53], v[206:209], v[166:169], v[50:53]
	v_mfma_f32_16x16x32_bf16 v[38:41], v[198:201], v[174:177], v[38:41]
	v_mfma_f32_16x16x32_bf16 v[34:37], v[206:209], v[174:177], v[34:37]
	v_mfma_f32_16x16x32_bf16 v[22:25], v[198:201], v[182:185], v[22:25]
	v_mfma_f32_16x16x32_bf16 v[18:21], v[206:209], v[182:185], v[18:21]
	v_mfma_f32_16x16x32_bf16 v[6:9], v[198:201], v[190:193], v[6:9]
	v_mfma_f32_16x16x32_bf16 v[2:5], v[206:209], v[190:193], v[2:5]
	v_mfma_f32_16x16x32_bf16 v[54:57], v[202:205], v[170:173], v[54:57]
	v_mfma_f32_16x16x32_bf16 v[50:53], v[210:213], v[170:173], v[50:53]
	v_mfma_f32_16x16x32_bf16 v[38:41], v[202:205], v[178:181], v[38:41]
	v_mfma_f32_16x16x32_bf16 v[34:37], v[210:213], v[178:181], v[34:37]
	v_mfma_f32_16x16x32_bf16 v[22:25], v[202:205], v[186:189], v[22:25]
	v_mfma_f32_16x16x32_bf16 v[18:21], v[210:213], v[186:189], v[18:21]
	v_mfma_f32_16x16x32_bf16 v[6:9], v[202:205], v[194:197], v[6:9]
	v_mfma_f32_16x16x32_bf16 v[2:5], v[210:213], v[194:197], v[2:5]
	s_add_i32 s23, s23, 2
	s_add_u32 s21, s21, 0x100
	s_addc_u32 s22, s22, 0
	s_cmp_gt_u32 s23, 41
	s_mov_b64 s[88:89], s[28:29]
	s_barrier
	s_cbranch_scc0 .LBB0_684
	s_cmp_eq_u64 s[38:39], 0
	s_cbranch_scc1 .Leinit684_skip
	v_lshl_add_u32 v246, s20, 8, v144
	v_lshl_or_b32 v247, s8, 8, v147
	v_lshlrev_b32_e32 v246, 11, v246
	v_lshl_add_u32 v246, v247, 1, v246
	global_load_dwordx4 v[166:169], v246, s[82:83]
	global_load_dwordx4 v[170:173], v246, s[82:83] offset:256
	s_add_u32 s24, s82, 0x8000
	s_addc_u32 s25, s83, 0
	global_load_dwordx4 v[174:177], v246, s[24:25]
	global_load_dwordx4 v[178:181], v246, s[24:25] offset:256
	s_add_u32 s24, s82, 0x10000
	s_addc_u32 s25, s83, 0
	global_load_dwordx4 v[182:185], v246, s[24:25]
	global_load_dwordx4 v[186:189], v246, s[24:25] offset:256
	s_add_u32 s24, s82, 0x18000
	s_addc_u32 s25, s83, 0
	global_load_dwordx4 v[190:193], v246, s[24:25]
	global_load_dwordx4 v[198:201], v246, s[24:25] offset:256
	s_add_u32 s24, s82, 0x40000
	s_addc_u32 s25, s83, 0
	global_load_dwordx4 v[194:197], v246, s[24:25]
	global_load_dwordx4 v[202:205], v246, s[24:25] offset:256
	s_add_u32 s24, s82, 0x48000
	s_addc_u32 s25, s83, 0
	global_load_dwordx4 v[206:209], v246, s[24:25]
	global_load_dwordx4 v[210:213], v246, s[24:25] offset:256
	s_add_u32 s24, s82, 0x50000
	s_addc_u32 s25, s83, 0
	global_load_dwordx4 v[214:217], v246, s[24:25]
	global_load_dwordx4 v[218:221], v246, s[24:25] offset:256
	s_add_u32 s24, s82, 0x58000
	s_addc_u32 s25, s83, 0
	global_load_dwordx4 v[238:241], v246, s[24:25]
	global_load_dwordx4 v[242:245], v246, s[24:25] offset:256
